# adds: w_out/ffn_down fused-norm epilogues: gpost/gnext gain loads hoisted out of the per-row ladders, residual loads of both column halves issued together (counted vmcnt)
# speedup vs baseline: 1.0328x; 1.0097x over previous
; #define LAS __attribute__((address_space(3)))
;     __device__ __forceinline__ void operator()(f32x4 (&acc)[2][2][4][2], const Unit& u, int wr, int wc, int fr, int fq) const {
;         const LAS float* S = (const LAS float*)(lds + EN_S);
;         const int col0 = u.pn * 256 + wc * 32 + 8 * fq;
;         exchange(acc, u, 0, wr, wc, fr, fq);
; #pragma unroll
;         for (int ai = 0; ai < 2; ++ai)
; #pragma unroll
;             for (int m = 0; m < 4; ++m) { const int rl = ai * 128 + wr * 64 + m * 16 + fr; const float r1 = S[rl]; const size_t off = (size_t)(u.pm * 256 + rl) * DM + col0;
; #pragma unroll
;                 for (int bj = 0; bj < 2; ++bj) { const f32x4 xa = *(const f32x4*)(xin + off + bj * 128), xb = *(const f32x4*)(xin + off + bj * 128 + 4);
;                     const f32x4 ga = *(const f32x4*)(gpost + col0 + bj * 128), gb = *(const f32x4*)(gpost + col0 + bj * 128 + 4);
;                     const f32x4 v0 = xa + acc[ai][bj][m][0] * r1 * ga, v1 = xb + acc[ai][bj][m][1] * r1 * gb;
;                     *(f32x4*)(xout + off + bj * 128) = v0; *(f32x4*)(xout + off + bj * 128 + 4) = v1; acc[ai][bj][m][0] = v0; acc[ai][bj][m][1] = v1; }
;                 asm volatile("" ::: "memory"); }
.LBB0_103:
	s_or_b64 exec, exec, s[84:85]
	s_lshl_b32 s54, s82, 8
	v_add_u32_e32 v144, s54, v170
	v_lshl_or_b32 v142, s78, 8, v190
	v_ashrrev_i32_e32 v145, 31, v144
	v_ashrrev_i32_e32 v143, 31, v142
	v_lshlrev_b64 v[146:147], 12, v[144:145]
	v_lshl_add_u64 v[146:147], s[34:35], 0, v[146:147]
	v_lshlrev_b64 v[158:159], 2, v[142:143]
	v_lshl_add_u64 v[160:161], v[146:147], 0, v[158:159]
	v_lshl_add_u64 v[154:155], s[52:53], 0, v[158:159]
	global_load_dwordx4 v[218:221], v[154:155], off
	global_load_dwordx4 v[222:225], v[154:155], off offset:16
	global_load_dwordx4 v[226:229], v[154:155], off offset:512
	global_load_dwordx4 v[230:233], v[154:155], off offset:528
	s_waitcnt lgkmcnt(0)
	s_barrier
	ds_read_b32 v156, v182
	global_load_dwordx4 v[146:149], v[160:161], off offset:16
	global_load_dwordx4 v[150:153], v[160:161], off
	global_load_dwordx4 v[234:237], v[160:161], off offset:528
	global_load_dwordx4 v[238:241], v[160:161], off offset:512
	s_andn2_b64 vcc, exec, s[62:63]
	s_waitcnt lgkmcnt(0)
	v_pk_mul_f32 v[52:53], v[52:53], v[156:157] op_sel_hi:[1,0]
	v_pk_mul_f32 v[50:51], v[50:51], v[156:157] op_sel_hi:[1,0]
	v_pk_mul_f32 v[56:57], v[56:57], v[156:157] op_sel_hi:[1,0]
	v_pk_mul_f32 v[54:55], v[54:55], v[156:157] op_sel_hi:[1,0]
	v_pk_mul_f32 v[58:59], v[58:59], v[156:157] op_sel_hi:[1,0]
	v_pk_mul_f32 v[64:65], v[64:65], v[156:157] op_sel_hi:[1,0]
	v_pk_mul_f32 v[62:63], v[62:63], v[156:157] op_sel_hi:[1,0]
	v_pk_mul_f32 v[60:61], v[60:61], v[156:157] op_sel_hi:[1,0]
	s_waitcnt vmcnt(3)
	v_pk_fma_f32 v[56:57], v[56:57], v[224:225], v[148:149]
	s_waitcnt vmcnt(2)
	v_pk_fma_f32 v[52:53], v[220:221], v[52:53], v[152:153]
	v_pk_fma_f32 v[50:51], v[218:219], v[50:51], v[150:151]
	v_pk_fma_f32 v[54:55], v[54:55], v[222:223], v[146:147]
	global_store_dwordx4 v[160:161], v[50:53], off
	global_store_dwordx4 v[160:161], v[54:57], off offset:16
	s_waitcnt vmcnt(3)
	v_pk_fma_f32 v[58:59], v[58:59], v[230:231], v[234:235]
	v_add_u32_e32 v146, s54, v173
	v_ashrrev_i32_e32 v147, 31, v146
	s_waitcnt vmcnt(2)
	v_pk_fma_f32 v[64:65], v[64:65], v[228:229], v[240:241]
	v_pk_fma_f32 v[62:63], v[62:63], v[226:227], v[238:239]
	v_pk_fma_f32 v[60:61], v[60:61], v[232:233], v[236:237]
	v_lshlrev_b64 v[148:149], 12, v[146:147]
	global_store_dwordx4 v[160:161], v[62:65], off offset:512
	global_store_dwordx4 v[160:161], v[58:61], off offset:528
	v_lshl_add_u64 v[148:149], s[34:35], 0, v[148:149]
	v_lshl_add_u64 v[156:157], v[148:149], 0, v[158:159]
	ds_read_b32 v152, v183
	global_load_dwordx4 v[148:151], v[156:157], off offset:16
	global_load_dwordx4 v[166:169], v[156:157], off
	global_load_dwordx4 v[234:237], v[156:157], off offset:528
	global_load_dwordx4 v[238:241], v[156:157], off offset:512
	s_waitcnt lgkmcnt(0)
	v_pk_mul_f32 v[76:77], v[76:77], v[152:153] op_sel_hi:[1,0]
	v_pk_mul_f32 v[74:75], v[74:75], v[152:153] op_sel_hi:[1,0]
	v_pk_mul_f32 v[80:81], v[80:81], v[152:153] op_sel_hi:[1,0]
	v_pk_mul_f32 v[78:79], v[78:79], v[152:153] op_sel_hi:[1,0]
	v_pk_mul_f32 v[90:91], v[90:91], v[152:153] op_sel_hi:[1,0]
	v_pk_mul_f32 v[96:97], v[96:97], v[152:153] op_sel_hi:[1,0]
	v_pk_mul_f32 v[94:95], v[94:95], v[152:153] op_sel_hi:[1,0]
	v_pk_mul_f32 v[92:93], v[92:93], v[152:153] op_sel_hi:[1,0]
	s_waitcnt vmcnt(3)
	v_pk_fma_f32 v[80:81], v[80:81], v[224:225], v[150:151]
	s_waitcnt vmcnt(2)
	v_pk_fma_f32 v[76:77], v[220:221], v[76:77], v[168:169]
	v_pk_fma_f32 v[74:75], v[218:219], v[74:75], v[166:167]
	v_pk_fma_f32 v[78:79], v[78:79], v[222:223], v[148:149]
	global_store_dwordx4 v[156:157], v[74:77], off
	global_store_dwordx4 v[156:157], v[78:81], off offset:16
	s_waitcnt vmcnt(3)
	v_pk_fma_f32 v[90:91], v[90:91], v[230:231], v[234:235]
	v_add_u32_e32 v148, s54, v174
	v_ashrrev_i32_e32 v149, 31, v148
	s_waitcnt vmcnt(2)
	v_pk_fma_f32 v[96:97], v[96:97], v[228:229], v[240:241]
	v_pk_fma_f32 v[94:95], v[94:95], v[226:227], v[238:239]
	v_pk_fma_f32 v[92:93], v[92:93], v[232:233], v[236:237]
	v_lshlrev_b64 v[150:151], 12, v[148:149]
	global_store_dwordx4 v[156:157], v[94:97], off offset:512
	global_store_dwordx4 v[156:157], v[90:93], off offset:528
	v_lshl_add_u64 v[150:151], s[34:35], 0, v[150:151]
	v_lshl_add_u64 v[160:161], v[150:151], 0, v[158:159]
	ds_read_b32 v156, v184
	global_load_dwordx4 v[150:153], v[160:161], off offset:16
	global_load_dwordx4 v[166:169], v[160:161], off
	global_load_dwordx4 v[234:237], v[160:161], off offset:528
	global_load_dwordx4 v[238:241], v[160:161], off offset:512
	s_waitcnt lgkmcnt(0)
	v_pk_mul_f32 v[100:101], v[100:101], v[156:157] op_sel_hi:[1,0]
	v_pk_mul_f32 v[98:99], v[98:99], v[156:157] op_sel_hi:[1,0]
	v_pk_mul_f32 v[104:105], v[104:105], v[156:157] op_sel_hi:[1,0]
	v_pk_mul_f32 v[102:103], v[102:103], v[156:157] op_sel_hi:[1,0]
	v_pk_mul_f32 v[114:115], v[114:115], v[156:157] op_sel_hi:[1,0]
	v_pk_mul_f32 v[120:121], v[120:121], v[156:157] op_sel_hi:[1,0]
	v_pk_mul_f32 v[118:119], v[118:119], v[156:157] op_sel_hi:[1,0]
	v_pk_mul_f32 v[116:117], v[116:117], v[156:157] op_sel_hi:[1,0]
	s_waitcnt vmcnt(3)
	v_pk_fma_f32 v[104:105], v[104:105], v[224:225], v[152:153]
	s_waitcnt vmcnt(2)
	v_pk_fma_f32 v[100:101], v[220:221], v[100:101], v[168:169]
	v_pk_fma_f32 v[98:99], v[218:219], v[98:99], v[166:167]
	v_pk_fma_f32 v[102:103], v[102:103], v[222:223], v[150:151]
	global_store_dwordx4 v[160:161], v[98:101], off
	global_store_dwordx4 v[160:161], v[102:105], off offset:16
	s_waitcnt vmcnt(3)
	v_pk_fma_f32 v[114:115], v[114:115], v[230:231], v[234:235]
	v_add_u32_e32 v150, s54, v175
	v_ashrrev_i32_e32 v151, 31, v150
	s_waitcnt vmcnt(2)
;     __device__ __forceinline__ void operator()(f32x4 (&acc)[2][2][4][2], const Unit& u, int wr, int wc, int fr, int fq) const {
;     ...
; #pragma unroll
;         for (int ai = 0; ai < 2; ++ai)
; #pragma unroll
;             for (int m = 0; m < 4; ++m) { const int rl = ai * 128 + wr * 64 + m * 16 + fr; const float r1 = S[rl]; const size_t off = (size_t)(u.pm * 256 + rl) * DM + col0;
; #pragma unroll
;                 for (int bj = 0; bj < 2; ++bj) { const f32x4 xa = *(const f32x4*)(xin + off + bj * 128), xb = *(const f32x4*)(xin + off + bj * 128 + 4);
;                     const f32x4 ga = *(const f32x4*)(gpost + col0 + bj * 128), gb = *(const f32x4*)(gpost + col0 + bj * 128 + 4);
;                     const f32x4 v0 = xa + acc[ai][bj][m][0] * r1 * ga, v1 = xb + acc[ai][bj][m][1] * r1 * gb;
;                     *(f32x4*)(xout + off + bj * 128) = v0; *(f32x4*)(xout + off + bj * 128 + 4) = v1; acc[ai][bj][m][0] = v0; acc[ai][bj][m][1] = v1; }
;                 asm volatile("" ::: "memory"); }
	v_pk_fma_f32 v[120:121], v[120:121], v[228:229], v[240:241]
	v_pk_fma_f32 v[118:119], v[118:119], v[226:227], v[238:239]
	v_lshlrev_b64 v[156:157], 12, v[150:151]
	v_pk_fma_f32 v[116:117], v[116:117], v[232:233], v[236:237]
	global_store_dwordx4 v[160:161], v[118:121], off offset:512
	global_store_dwordx4 v[160:161], v[114:117], off offset:528
	v_lshl_add_u64 v[156:157], s[34:35], 0, v[156:157]
	v_lshl_add_u64 v[156:157], v[156:157], 0, v[158:159]
	ds_read_b32 v152, v185
	global_load_dwordx4 v[166:169], v[156:157], off offset:16
	global_load_dwordx4 v[202:205], v[156:157], off
	global_load_dwordx4 v[234:237], v[156:157], off offset:528
	global_load_dwordx4 v[238:241], v[156:157], off offset:512
	s_waitcnt lgkmcnt(0)
	v_pk_mul_f32 v[128:129], v[128:129], v[152:153] op_sel_hi:[1,0]
	v_pk_mul_f32 v[126:127], v[126:127], v[152:153] op_sel_hi:[1,0]
	v_pk_mul_f32 v[124:125], v[124:125], v[152:153] op_sel_hi:[1,0]
	v_pk_mul_f32 v[122:123], v[122:123], v[152:153] op_sel_hi:[1,0]
	v_pk_mul_f32 v[112:113], v[112:113], v[152:153] op_sel_hi:[1,0]
	v_pk_mul_f32 v[110:111], v[110:111], v[152:153] op_sel_hi:[1,0]
	v_pk_mul_f32 v[108:109], v[108:109], v[152:153] op_sel_hi:[1,0]
	v_pk_mul_f32 v[106:107], v[106:107], v[152:153] op_sel_hi:[1,0]
	v_add_u32_e32 v152, s54, v176
	v_ashrrev_i32_e32 v153, 31, v152
	v_lshlrev_b64 v[160:161], 12, v[152:153]
	v_lshl_add_u64 v[160:161], s[34:35], 0, v[160:161]
	v_lshl_add_u64 v[160:161], v[160:161], 0, v[158:159]
	s_waitcnt vmcnt(3)
	v_pk_fma_f32 v[124:125], v[124:125], v[224:225], v[168:169]
	s_waitcnt vmcnt(2)
	v_pk_fma_f32 v[128:129], v[220:221], v[128:129], v[204:205]
	v_pk_fma_f32 v[126:127], v[218:219], v[126:127], v[202:203]
	v_pk_fma_f32 v[122:123], v[122:123], v[222:223], v[166:167]
	global_store_dwordx4 v[156:157], v[126:129], off
	global_store_dwordx4 v[156:157], v[122:125], off offset:16
	s_waitcnt vmcnt(3)
	v_pk_fma_f32 v[108:109], v[108:109], v[232:233], v[236:237]
	s_waitcnt vmcnt(2)
	v_pk_fma_f32 v[112:113], v[112:113], v[228:229], v[240:241]
	v_pk_fma_f32 v[110:111], v[110:111], v[226:227], v[238:239]
	v_pk_fma_f32 v[106:107], v[106:107], v[230:231], v[234:235]
	global_store_dwordx4 v[156:157], v[110:113], off offset:512
	global_store_dwordx4 v[156:157], v[106:109], off offset:528
	ds_read_b32 v156, v186
	global_load_dwordx4 v[166:169], v[160:161], off offset:16
	global_load_dwordx4 v[202:205], v[160:161], off
	global_load_dwordx4 v[234:237], v[160:161], off offset:528
	global_load_dwordx4 v[238:241], v[160:161], off offset:512
	s_waitcnt lgkmcnt(0)
	v_pk_mul_f32 v[88:89], v[88:89], v[156:157] op_sel_hi:[1,0]
	v_pk_mul_f32 v[86:87], v[86:87], v[156:157] op_sel_hi:[1,0]
	v_pk_mul_f32 v[84:85], v[84:85], v[156:157] op_sel_hi:[1,0]
	v_pk_mul_f32 v[82:83], v[82:83], v[156:157] op_sel_hi:[1,0]
	v_pk_mul_f32 v[72:73], v[72:73], v[156:157] op_sel_hi:[1,0]
	v_pk_mul_f32 v[70:71], v[70:71], v[156:157] op_sel_hi:[1,0]
	v_pk_mul_f32 v[68:69], v[68:69], v[156:157] op_sel_hi:[1,0]
	v_pk_mul_f32 v[66:67], v[66:67], v[156:157] op_sel_hi:[1,0]
	v_add_u32_e32 v156, s54, v177
	v_ashrrev_i32_e32 v157, 31, v156
	v_lshlrev_b64 v[162:163], 12, v[156:157]
	v_lshl_add_u64 v[162:163], s[34:35], 0, v[162:163]
	v_lshl_add_u64 v[162:163], v[162:163], 0, v[158:159]
	s_waitcnt vmcnt(3)
	v_pk_fma_f32 v[84:85], v[84:85], v[224:225], v[168:169]
	s_waitcnt vmcnt(2)
	v_pk_fma_f32 v[88:89], v[220:221], v[88:89], v[204:205]
	v_pk_fma_f32 v[86:87], v[218:219], v[86:87], v[202:203]
	v_pk_fma_f32 v[82:83], v[82:83], v[222:223], v[166:167]
	global_store_dwordx4 v[160:161], v[86:89], off
	global_store_dwordx4 v[160:161], v[82:85], off offset:16
	s_waitcnt vmcnt(3)
	v_pk_fma_f32 v[68:69], v[68:69], v[232:233], v[236:237]
	s_waitcnt vmcnt(2)
	v_pk_fma_f32 v[72:73], v[72:73], v[228:229], v[240:241]
	v_pk_fma_f32 v[70:71], v[70:71], v[226:227], v[238:239]
	v_pk_fma_f32 v[66:67], v[66:67], v[230:231], v[234:235]
	global_store_dwordx4 v[160:161], v[70:73], off offset:512
	global_store_dwordx4 v[160:161], v[66:69], off offset:528
	ds_read_b32 v160, v187
	global_load_dwordx4 v[166:169], v[162:163], off offset:16
	global_load_dwordx4 v[202:205], v[162:163], off
	global_load_dwordx4 v[234:237], v[162:163], off offset:528
	global_load_dwordx4 v[238:241], v[162:163], off offset:512
	s_waitcnt lgkmcnt(0)
	v_pk_mul_f32 v[48:49], v[48:49], v[160:161] op_sel_hi:[1,0]
	v_pk_mul_f32 v[46:47], v[46:47], v[160:161] op_sel_hi:[1,0]
	v_pk_mul_f32 v[44:45], v[44:45], v[160:161] op_sel_hi:[1,0]
	v_pk_mul_f32 v[42:43], v[42:43], v[160:161] op_sel_hi:[1,0]
	v_pk_mul_f32 v[34:35], v[34:35], v[160:161] op_sel_hi:[1,0]
	v_pk_mul_f32 v[40:41], v[40:41], v[160:161] op_sel_hi:[1,0]
	v_pk_mul_f32 v[38:39], v[38:39], v[160:161] op_sel_hi:[1,0]
	v_pk_mul_f32 v[36:37], v[36:37], v[160:161] op_sel_hi:[1,0]
	s_waitcnt vmcnt(3)
	v_pk_fma_f32 v[44:45], v[44:45], v[224:225], v[168:169]
	s_waitcnt vmcnt(2)
	v_pk_fma_f32 v[48:49], v[220:221], v[48:49], v[204:205]
	v_pk_fma_f32 v[46:47], v[218:219], v[46:47], v[202:203]
	v_pk_fma_f32 v[42:43], v[42:43], v[222:223], v[166:167]
	global_store_dwordx4 v[162:163], v[46:49], off
	global_store_dwordx4 v[162:163], v[42:45], off offset:16
	s_waitcnt vmcnt(3)
	v_pk_fma_f32 v[34:35], v[34:35], v[230:231], v[234:235]
	v_add_u32_e32 v166, s54, v178
	s_waitcnt vmcnt(2)
; __device__ __forceinline__ float swap_add(float v) { auto rr = __builtin_amdgcn_permlane32_swap(__float_as_uint(v), __float_as_uint(v), false, false); return __uint_as_float(rr[0]) + __uint_as_float(rr[1]); }
;     __device__ __forceinline__ void exchange(const f32x4 (&acc)[2][2][4][2], const Unit& u, int e, int wr, int wc, int fr, int fq) const {
;     ...
;             for (int m = 0; m < 4; ++m) { float q = 0.f;
; #pragma unroll
;                 for (int bj = 0; bj < 2; ++bj)
; #pragma unroll
;                     for (int n = 0; n < 2; ++n) { const f32x4 v = acc[ai][bj][m][n]; q += (v[0] * v[0] + v[1] * v[1]) + (v[2] * v[2] + v[3] * v[3]); }
;                 q += __int_as_float(__builtin_amdgcn_ds_bpermute((lid ^ 16) << 2, __float_as_int(q))); q = swap_add(q);
;                 if (fq == 0) P[(ai * 128 + wr * 64 + m * 16 + fr) * 4 + wc] = q; }
;     __device__ __forceinline__ void operator()(f32x4 (&acc)[2][2][4][2], const Unit& u, int wr, int wc, int fr, int fq) const {
;     ...
; #pragma unroll
;         for (int ai = 0; ai < 2; ++ai)
; #pragma unroll
;             for (int m = 0; m < 4; ++m) { const int rl = ai * 128 + wr * 64 + m * 16 + fr; const float r1 = S[rl]; const size_t off = (size_t)(u.pm * 256 + rl) * DM + col0;
; #pragma unroll
;                 for (int bj = 0; bj < 2; ++bj) { const f32x4 xa = *(const f32x4*)(xin + off + bj * 128), xb = *(const f32x4*)(xin + off + bj * 128 + 4);
;                     const f32x4 ga = *(const f32x4*)(gpost + col0 + bj * 128), gb = *(const f32x4*)(gpost + col0 + bj * 128 + 4);
;                     const f32x4 v0 = xa + acc[ai][bj][m][0] * r1 * ga, v1 = xb + acc[ai][bj][m][1] * r1 * gb;
;                     *(f32x4*)(xout + off + bj * 128) = v0; *(f32x4*)(xout + off + bj * 128 + 4) = v1; acc[ai][bj][m][0] = v0; acc[ai][bj][m][1] = v1; }
;                 asm volatile("" ::: "memory"); }
;         if (gnext) {
;             exchange(acc, u, 1, wr, wc, fr, fq);
	v_pk_fma_f32 v[40:41], v[40:41], v[228:229], v[240:241]
	v_pk_fma_f32 v[38:39], v[38:39], v[226:227], v[238:239]
	v_ashrrev_i32_e32 v167, 31, v166
	v_pk_fma_f32 v[36:37], v[36:37], v[232:233], v[236:237]
	global_store_dwordx4 v[162:163], v[38:41], off offset:512
	global_store_dwordx4 v[162:163], v[34:37], off offset:528
	v_lshlrev_b64 v[162:163], 12, v[166:167]
	v_lshl_add_u64 v[162:163], s[34:35], 0, v[162:163]
	v_lshl_add_u64 v[162:163], v[162:163], 0, v[158:159]
	ds_read_b32 v160, v188
	global_load_dwordx4 v[202:205], v[162:163], off offset:16
	global_load_dwordx4 v[206:209], v[162:163], off
	global_load_dwordx4 v[234:237], v[162:163], off offset:528
	global_load_dwordx4 v[238:241], v[162:163], off offset:512
	v_add_u32_e32 v168, s54, v179
	v_ashrrev_i32_e32 v169, 31, v168
	s_waitcnt lgkmcnt(0)
	v_pk_mul_f32 v[32:33], v[32:33], v[160:161] op_sel_hi:[1,0]
	v_pk_mul_f32 v[30:31], v[30:31], v[160:161] op_sel_hi:[1,0]
	v_pk_mul_f32 v[28:29], v[28:29], v[160:161] op_sel_hi:[1,0]
	v_pk_mul_f32 v[26:27], v[26:27], v[160:161] op_sel_hi:[1,0]
	v_pk_mul_f32 v[24:25], v[24:25], v[160:161] op_sel_hi:[1,0]
	v_pk_mul_f32 v[22:23], v[22:23], v[160:161] op_sel_hi:[1,0]
	v_pk_mul_f32 v[20:21], v[20:21], v[160:161] op_sel_hi:[1,0]
	v_pk_mul_f32 v[18:19], v[18:19], v[160:161] op_sel_hi:[1,0]
	s_waitcnt vmcnt(3)
	v_pk_fma_f32 v[28:29], v[28:29], v[224:225], v[204:205]
	s_waitcnt vmcnt(2)
	v_pk_fma_f32 v[32:33], v[220:221], v[32:33], v[208:209]
	v_pk_fma_f32 v[30:31], v[218:219], v[30:31], v[206:207]
	v_pk_fma_f32 v[26:27], v[26:27], v[222:223], v[202:203]
	global_store_dwordx4 v[162:163], v[30:33], off
	global_store_dwordx4 v[162:163], v[26:29], off offset:16
	s_waitcnt vmcnt(3)
	v_pk_fma_f32 v[20:21], v[20:21], v[232:233], v[236:237]
	s_waitcnt vmcnt(2)
	v_pk_fma_f32 v[24:25], v[24:25], v[228:229], v[240:241]
	v_pk_fma_f32 v[22:23], v[22:23], v[226:227], v[238:239]
	v_pk_fma_f32 v[18:19], v[18:19], v[230:231], v[234:235]
	global_store_dwordx4 v[162:163], v[22:25], off offset:512
	global_store_dwordx4 v[162:163], v[18:21], off offset:528
	v_lshlrev_b64 v[162:163], 12, v[168:169]
	v_lshl_add_u64 v[162:163], s[34:35], 0, v[162:163]
	v_lshl_add_u64 v[158:159], v[162:163], 0, v[158:159]
	ds_read_b32 v160, v189
	global_load_dwordx4 v[202:205], v[158:159], off offset:16
	global_load_dwordx4 v[206:209], v[158:159], off
	global_load_dwordx4 v[234:237], v[158:159], off offset:528
	global_load_dwordx4 v[238:241], v[158:159], off offset:512
	s_waitcnt lgkmcnt(0)
	v_pk_mul_f32 v[16:17], v[16:17], v[160:161] op_sel_hi:[1,0]
	v_pk_mul_f32 v[14:15], v[14:15], v[160:161] op_sel_hi:[1,0]
	v_pk_mul_f32 v[12:13], v[12:13], v[160:161] op_sel_hi:[1,0]
	v_pk_mul_f32 v[10:11], v[10:11], v[160:161] op_sel_hi:[1,0]
	v_pk_mul_f32 v[8:9], v[8:9], v[160:161] op_sel_hi:[1,0]
	v_pk_mul_f32 v[6:7], v[6:7], v[160:161] op_sel_hi:[1,0]
	v_pk_mul_f32 v[4:5], v[4:5], v[160:161] op_sel_hi:[1,0]
	v_pk_mul_f32 v[2:3], v[2:3], v[160:161] op_sel_hi:[1,0]
	s_waitcnt vmcnt(3)
	v_pk_fma_f32 v[12:13], v[12:13], v[224:225], v[204:205]
	s_waitcnt vmcnt(2)
	v_pk_fma_f32 v[16:17], v[220:221], v[16:17], v[208:209]
	v_pk_fma_f32 v[14:15], v[218:219], v[14:15], v[206:207]
	v_pk_fma_f32 v[10:11], v[10:11], v[222:223], v[202:203]
	global_store_dwordx4 v[158:159], v[14:17], off
	global_store_dwordx4 v[158:159], v[10:13], off offset:16
	s_waitcnt vmcnt(3)
	v_pk_fma_f32 v[4:5], v[4:5], v[232:233], v[236:237]
	s_waitcnt vmcnt(2)
	v_pk_fma_f32 v[8:9], v[8:9], v[228:229], v[240:241]
	v_pk_fma_f32 v[6:7], v[6:7], v[226:227], v[238:239]
	v_pk_fma_f32 v[2:3], v[2:3], v[230:231], v[234:235]
	global_store_dwordx4 v[158:159], v[6:9], off offset:512
	global_store_dwordx4 v[158:159], v[2:5], off offset:528
	s_cbranch_vccnz .LBB0_140
	v_mul_f32_e32 v154, v51, v51
	v_mul_f32_e32 v155, v53, v53
	v_fmac_f32_e32 v154, v50, v50
	v_fmac_f32_e32 v155, v52, v52
	v_add_f32_e32 v154, v154, v155
	v_mul_f32_e32 v155, v55, v55
	v_mul_f32_e32 v158, v57, v57
	v_fmac_f32_e32 v155, v54, v54
	v_fmac_f32_e32 v158, v56, v56
	v_add_f32_e32 v155, v155, v158
	v_add_f32_e32 v154, v154, v155
	v_mul_f32_e32 v155, v63, v63
	v_mul_f32_e32 v158, v65, v65
	v_fmac_f32_e32 v155, v62, v62
	v_fmac_f32_e32 v158, v64, v64
	v_add_f32_e32 v155, v155, v158
	v_add_f32_e32 v154, v154, v155
	v_mul_f32_e32 v155, v59, v59
	v_mul_f32_e32 v158, v61, v61
	v_fmac_f32_e32 v155, v58, v58
	v_fmac_f32_e32 v158, v60, v60
	v_add_f32_e32 v155, v155, v158
	v_add_f32_e32 v154, v154, v155
	ds_bpermute_b32 v155, v172, v154
	s_waitcnt lgkmcnt(0)
	v_add_f32_e32 v154, v154, v155
	v_mov_b32_e32 v155, v154
	s_nop 1
	v_permlane32_swap_b32_e32 v154, v155
	s_and_saveexec_b64 s[54:55], s[42:43]
	v_add_f32_e32 v154, v154, v155
	ds_write_b32 v201, v154
	s_or_b64 exec, exec, s[54:55]
	v_mul_f32_e32 v154, v75, v75
	v_mul_f32_e32 v155, v77, v77
	v_fmac_f32_e32 v154, v74, v74
	v_fmac_f32_e32 v155, v76, v76
	v_add_f32_e32 v154, v154, v155
	v_mul_f32_e32 v155, v79, v79
	v_mul_f32_e32 v158, v81, v81
	v_fmac_f32_e32 v155, v78, v78
	v_fmac_f32_e32 v158, v80, v80
	v_add_f32_e32 v155, v155, v158
	v_add_f32_e32 v154, v154, v155
	v_mul_f32_e32 v155, v95, v95
	v_mul_f32_e32 v158, v97, v97
	v_fmac_f32_e32 v155, v94, v94
	v_fmac_f32_e32 v158, v96, v96
	v_add_f32_e32 v155, v155, v158
	v_add_f32_e32 v154, v154, v155
	v_mul_f32_e32 v155, v91, v91
	v_mul_f32_e32 v158, v93, v93
	v_fmac_f32_e32 v155, v90, v90
	v_fmac_f32_e32 v158, v92, v92
	v_add_f32_e32 v155, v155, v158
	v_add_f32_e32 v154, v154, v155
	ds_bpermute_b32 v155, v172, v154
	s_waitcnt lgkmcnt(0)
; __device__ __forceinline__ float swap_add(float v) { auto rr = __builtin_amdgcn_permlane32_swap(__float_as_uint(v), __float_as_uint(v), false, false); return __uint_as_float(rr[0]) + __uint_as_float(rr[1]); }
;     __device__ __forceinline__ void exchange(const f32x4 (&acc)[2][2][4][2], const Unit& u, int e, int wr, int wc, int fr, int fq) const {
;     ...
;             for (int m = 0; m < 4; ++m) { float q = 0.f;
; #pragma unroll
;                 for (int bj = 0; bj < 2; ++bj)
; #pragma unroll
;                     for (int n = 0; n < 2; ++n) { const f32x4 v = acc[ai][bj][m][n]; q += (v[0] * v[0] + v[1] * v[1]) + (v[2] * v[2] + v[3] * v[3]); }
;                 q += __int_as_float(__builtin_amdgcn_ds_bpermute((lid ^ 16) << 2, __float_as_int(q))); q = swap_add(q);
;                 if (fq == 0) P[(ai * 128 + wr * 64 + m * 16 + fr) * 4 + wc] = q; }
;         __syncthreads();
;         float* xb = xbuf + (size_t)e * T * 4 + (size_t)u.pm * 256 * 4; unsigned* c = cnt + (e * 64 + u.pm) * 64;
;         if (tid < 256) { const float tot = (P[tid * 4] + P[tid * 4 + 1]) + (P[tid * 4 + 2] + P[tid * 4 + 3]);
;             __hip_atomic_store(xb + tid * 4 + u.pn, tot, __ATOMIC_RELAXED, __HIP_MEMORY_SCOPE_AGENT); }
	v_add_f32_e32 v154, v154, v155
	v_mov_b32_e32 v155, v154
	s_nop 1
	v_permlane32_swap_b32_e32 v154, v155
	s_and_saveexec_b64 s[54:55], s[42:43]
	v_add_f32_e32 v154, v154, v155
	ds_write_b32 v201, v154 offset:256
	s_or_b64 exec, exec, s[54:55]
	v_mul_f32_e32 v154, v99, v99
	v_mul_f32_e32 v155, v101, v101
	v_fmac_f32_e32 v154, v98, v98
	v_fmac_f32_e32 v155, v100, v100
	v_add_f32_e32 v154, v154, v155
	v_mul_f32_e32 v155, v103, v103
	v_mul_f32_e32 v158, v105, v105
	v_fmac_f32_e32 v155, v102, v102
	v_fmac_f32_e32 v158, v104, v104
	v_add_f32_e32 v155, v155, v158
	v_add_f32_e32 v154, v154, v155
	v_mul_f32_e32 v155, v119, v119
	v_mul_f32_e32 v158, v121, v121
	v_fmac_f32_e32 v155, v118, v118
	v_fmac_f32_e32 v158, v120, v120
	v_add_f32_e32 v155, v155, v158
	v_add_f32_e32 v154, v154, v155
	v_mul_f32_e32 v155, v115, v115
	v_mul_f32_e32 v158, v117, v117
	v_fmac_f32_e32 v155, v114, v114
	v_fmac_f32_e32 v158, v116, v116
	v_add_f32_e32 v155, v155, v158
	v_add_f32_e32 v154, v154, v155
	ds_bpermute_b32 v155, v172, v154
	s_waitcnt lgkmcnt(0)
	v_add_f32_e32 v154, v154, v155
	v_mov_b32_e32 v155, v154
	s_nop 1
	v_permlane32_swap_b32_e32 v154, v155
	s_and_saveexec_b64 s[54:55], s[42:43]
	v_add_f32_e32 v154, v154, v155
	ds_write_b32 v201, v154 offset:512
	s_or_b64 exec, exec, s[54:55]
	v_mul_f32_e32 v154, v127, v127
	v_mul_f32_e32 v155, v129, v129
	v_fmac_f32_e32 v154, v126, v126
	v_fmac_f32_e32 v155, v128, v128
	v_add_f32_e32 v154, v154, v155
	v_mul_f32_e32 v155, v123, v123
	v_mul_f32_e32 v158, v125, v125
	v_fmac_f32_e32 v155, v122, v122
	v_fmac_f32_e32 v158, v124, v124
	v_add_f32_e32 v155, v155, v158
	v_add_f32_e32 v154, v154, v155
	v_mul_f32_e32 v155, v111, v111
	v_mul_f32_e32 v158, v113, v113
	v_fmac_f32_e32 v155, v110, v110
	v_fmac_f32_e32 v158, v112, v112
	v_add_f32_e32 v155, v155, v158
	v_add_f32_e32 v154, v154, v155
	v_mul_f32_e32 v155, v107, v107
	v_mul_f32_e32 v158, v109, v109
	v_fmac_f32_e32 v155, v106, v106
	v_fmac_f32_e32 v158, v108, v108
	v_add_f32_e32 v155, v155, v158
	v_add_f32_e32 v154, v154, v155
	ds_bpermute_b32 v155, v172, v154
	s_waitcnt lgkmcnt(0)
	v_add_f32_e32 v154, v154, v155
	v_mov_b32_e32 v155, v154
	s_nop 1
	v_permlane32_swap_b32_e32 v154, v155
	s_and_saveexec_b64 s[54:55], s[42:43]
	v_add_f32_e32 v154, v154, v155
	ds_write_b32 v201, v154 offset:768
	s_or_b64 exec, exec, s[54:55]
	v_mul_f32_e32 v154, v87, v87
	v_mul_f32_e32 v155, v89, v89
	v_fmac_f32_e32 v154, v86, v86
	v_fmac_f32_e32 v155, v88, v88
	v_add_f32_e32 v154, v154, v155
	v_mul_f32_e32 v155, v83, v83
	v_mul_f32_e32 v158, v85, v85
	v_fmac_f32_e32 v155, v82, v82
	v_fmac_f32_e32 v158, v84, v84
	v_add_f32_e32 v155, v155, v158
	v_add_f32_e32 v154, v154, v155
	v_mul_f32_e32 v155, v71, v71
	v_mul_f32_e32 v158, v73, v73
	v_fmac_f32_e32 v155, v70, v70
	v_fmac_f32_e32 v158, v72, v72
	v_add_f32_e32 v155, v155, v158
	v_add_f32_e32 v154, v154, v155
	v_mul_f32_e32 v155, v67, v67
	v_mul_f32_e32 v158, v69, v69
	v_fmac_f32_e32 v155, v66, v66
	v_fmac_f32_e32 v158, v68, v68
	v_add_f32_e32 v155, v155, v158
	v_add_f32_e32 v154, v154, v155
	ds_bpermute_b32 v155, v172, v154
	s_waitcnt lgkmcnt(0)
	v_add_f32_e32 v154, v154, v155
	v_mov_b32_e32 v155, v154
	s_nop 1
	v_permlane32_swap_b32_e32 v154, v155
	s_and_saveexec_b64 s[54:55], s[42:43]
	v_add_f32_e32 v154, v154, v155
	ds_write_b32 v201, v154 offset:2048
	s_or_b64 exec, exec, s[54:55]
	v_mul_f32_e32 v154, v47, v47
	v_mul_f32_e32 v155, v49, v49
	v_fmac_f32_e32 v154, v46, v46
	v_fmac_f32_e32 v155, v48, v48
	v_add_f32_e32 v154, v154, v155
	v_mul_f32_e32 v155, v43, v43
	v_mul_f32_e32 v158, v45, v45
	v_fmac_f32_e32 v155, v42, v42
	v_fmac_f32_e32 v158, v44, v44
	v_add_f32_e32 v155, v155, v158
	v_add_f32_e32 v154, v154, v155
	v_mul_f32_e32 v155, v39, v39
	v_mul_f32_e32 v158, v41, v41
	v_fmac_f32_e32 v155, v38, v38
	v_fmac_f32_e32 v158, v40, v40
	v_add_f32_e32 v155, v155, v158
	v_add_f32_e32 v154, v154, v155
	v_mul_f32_e32 v155, v35, v35
	v_mul_f32_e32 v158, v37, v37
	v_fmac_f32_e32 v155, v34, v34
	v_fmac_f32_e32 v158, v36, v36
	v_add_f32_e32 v155, v155, v158
	v_add_f32_e32 v154, v154, v155
	ds_bpermute_b32 v155, v172, v154
	s_waitcnt lgkmcnt(0)
	v_add_f32_e32 v154, v154, v155
	v_mov_b32_e32 v155, v154
	s_nop 1
	v_permlane32_swap_b32_e32 v154, v155
	s_and_saveexec_b64 s[54:55], s[42:43]
	v_add_f32_e32 v154, v154, v155
	ds_write_b32 v201, v154 offset:2304
	s_or_b64 exec, exec, s[54:55]
	v_mul_f32_e32 v154, v31, v31
	v_mul_f32_e32 v155, v33, v33
	v_fmac_f32_e32 v154, v30, v30
	v_fmac_f32_e32 v155, v32, v32
	v_add_f32_e32 v154, v154, v155
	v_mul_f32_e32 v155, v27, v27
	v_mul_f32_e32 v158, v29, v29
	v_fmac_f32_e32 v155, v26, v26
	v_fmac_f32_e32 v158, v28, v28
	v_add_f32_e32 v155, v155, v158
	v_add_f32_e32 v154, v154, v155
	v_mul_f32_e32 v155, v23, v23
	v_mul_f32_e32 v158, v25, v25
	v_fmac_f32_e32 v155, v22, v22
	v_fmac_f32_e32 v158, v24, v24
	v_add_f32_e32 v155, v155, v158
	v_add_f32_e32 v154, v154, v155
	v_mul_f32_e32 v155, v19, v19
	v_mul_f32_e32 v158, v21, v21
	v_fmac_f32_e32 v155, v18, v18
	v_fmac_f32_e32 v158, v20, v20
	v_add_f32_e32 v155, v155, v158
	v_add_f32_e32 v154, v154, v155
	ds_bpermute_b32 v155, v172, v154
	s_waitcnt lgkmcnt(0)
	v_add_f32_e32 v154, v154, v155
	v_mov_b32_e32 v155, v154
	s_nop 1
	v_permlane32_swap_b32_e32 v154, v155
	s_and_saveexec_b64 s[54:55], s[42:43]
	v_add_f32_e32 v154, v154, v155
	ds_write_b32 v201, v154 offset:2560
	s_or_b64 exec, exec, s[54:55]
	v_mul_f32_e32 v154, v15, v15
	v_mul_f32_e32 v155, v17, v17
	v_fmac_f32_e32 v154, v14, v14
	v_fmac_f32_e32 v155, v16, v16
	v_add_f32_e32 v154, v154, v155
	v_mul_f32_e32 v155, v11, v11
	v_mul_f32_e32 v158, v13, v13
	v_fmac_f32_e32 v155, v10, v10
	v_fmac_f32_e32 v158, v12, v12
	v_add_f32_e32 v155, v155, v158
	v_add_f32_e32 v154, v154, v155
	v_mul_f32_e32 v155, v7, v7
	v_mul_f32_e32 v158, v9, v9
	v_fmac_f32_e32 v155, v6, v6
	v_fmac_f32_e32 v158, v8, v8
	v_add_f32_e32 v155, v155, v158
	v_add_f32_e32 v154, v154, v155
	v_mul_f32_e32 v155, v3, v3
	v_mul_f32_e32 v158, v5, v5
	v_fmac_f32_e32 v155, v2, v2
	v_fmac_f32_e32 v158, v4, v4
	v_add_f32_e32 v155, v155, v158
	v_add_f32_e32 v154, v154, v155
	ds_bpermute_b32 v155, v172, v154
	s_waitcnt lgkmcnt(0)
	v_add_f32_e32 v154, v154, v155
	v_mov_b32_e32 v155, v154
	s_nop 1
	v_permlane32_swap_b32_e32 v154, v155
	s_and_saveexec_b64 s[54:55], s[42:43]
	v_add_f32_e32 v154, v154, v155
	ds_write_b32 v201, v154 offset:2816
	s_or_b64 exec, exec, s[54:55]
	s_add_u32 s12, s92, s12
	s_addc_u32 s13, s94, s13
	v_lshl_add_u64 v[154:155], v[136:137], 2, s[12:13]
	s_waitcnt lgkmcnt(0)
	s_barrier
	s_and_saveexec_b64 s[12:13], s[44:45]
	s_cbranch_execz .LBB0_122
	ds_read_b128 v[202:205], v180
	s_ashr_i32 s79, s78, 31
	v_lshl_add_u64 v[160:161], s[78:79], 2, v[154:155]
	s_waitcnt lgkmcnt(0)
	v_mov_b32_e32 v158, v203
	v_mov_b32_e32 v159, v204
	v_mov_b32_e32 v203, v205
	v_pk_add_f32 v[158:159], v[158:159], v[202:203]
	s_nop 0
	v_pk_add_f32 v[158:159], v[158:159], v[158:159] op_sel:[0,1] op_sel_hi:[1,0]
	global_store_dword v[160:161], v158, off sc1

; __device__ __forceinline__ unsigned cvt_pk_bf16(float lo, float hi) { const f32x2 v = {lo, hi}; const bf16x2_t b = __builtin_convertvector(v, bf16x2_t); return __builtin_bit_cast(unsigned, b); }
;     __device__ __forceinline__ void operator()(f32x4 (&acc)[2][2][4][2], const Unit& u, int wr, int wc, int fr, int fq) const {
;     ...
;         if (gnext) {
;             exchange(acc, u, 1, wr, wc, fr, fq);
; #pragma unroll
;             for (int ai = 0; ai < 2; ++ai)
; #pragma unroll
;                 for (int m = 0; m < 4; ++m) { const int rl = ai * 128 + wr * 64 + m * 16 + fr; const float r2 = S[rl]; const size_t off = (size_t)(u.pm * 256 + rl) * DM + col0;
; #pragma unroll
;                     for (int bj = 0; bj < 2; ++bj) { const f32x4 ga = *(const f32x4*)(gnext + col0 + bj * 128), gb = *(const f32x4*)(gnext + col0 + bj * 128 + 4);
;                         const f32x4 v0 = acc[ai][bj][m][0] * r2 * ga, v1 = acc[ai][bj][m][1] * r2 * gb;
;                         u32x4 w; w.x = cvt_pk_bf16(v0[0], v0[1]); w.y = cvt_pk_bf16(v0[2], v0[3]); w.z = cvt_pk_bf16(v1[0], v1[1]); w.w = cvt_pk_bf16(v1[2], v1[3]);
;                         *(u32x4*)(XN + off + bj * 128) = w; }
;                     asm volatile("" ::: "memory"); }
.LBB0_139:
	s_or_b64 exec, exec, s[12:13]
	v_lshl_add_u64 v[154:155], v[142:143], 2, s[14:15]
	global_load_dwordx4 v[234:237], v[154:155], off
	global_load_dwordx4 v[238:241], v[154:155], off offset:16
	global_load_dwordx4 v[242:245], v[154:155], off offset:512
	global_load_dwordx4 v[246:249], v[154:155], off offset:528
	s_waitcnt lgkmcnt(0)
	s_waitcnt vmcnt(0)
	s_barrier
	ds_read_b32 v158, v182
	v_lshlrev_b64 v[144:145], 11, v[144:145]
	v_lshlrev_b64 v[142:143], 1, v[142:143]
	v_lshl_add_u64 v[144:145], s[4:5], 0, v[144:145]
	v_lshl_add_u64 v[144:145], v[144:145], 0, v[142:143]
	s_waitcnt lgkmcnt(0)
	v_pk_mul_f32 v[52:53], v[52:53], v[158:159] op_sel_hi:[1,0]
	v_pk_mul_f32 v[50:51], v[50:51], v[158:159] op_sel_hi:[1,0]
	v_pk_mul_f32 v[56:57], v[56:57], v[158:159] op_sel_hi:[1,0]
	v_pk_mul_f32 v[54:55], v[54:55], v[158:159] op_sel_hi:[1,0]
	v_pk_mul_f32 v[64:65], v[64:65], v[158:159] op_sel_hi:[1,0]
	v_pk_mul_f32 v[62:63], v[62:63], v[158:159] op_sel_hi:[1,0]
	v_pk_mul_f32 v[60:61], v[60:61], v[158:159] op_sel_hi:[1,0]
	v_pk_mul_f32 v[58:59], v[58:59], v[158:159] op_sel_hi:[1,0]
	v_pk_mul_f32 v[52:53], v[236:237], v[52:53]
	v_pk_mul_f32 v[50:51], v[234:235], v[50:51]
	v_pk_mul_f32 v[56:57], v[240:241], v[56:57]
	v_pk_mul_f32 v[54:55], v[238:239], v[54:55]
	v_cvt_pk_bf16_f32 v50, v50, v51
	v_cvt_pk_bf16_f32 v51, v52, v53
	v_cvt_pk_bf16_f32 v52, v54, v55
	v_cvt_pk_bf16_f32 v53, v56, v57
	global_store_dwordx4 v[144:145], v[50:53], off
	s_nop 0
	s_nop 0
	v_pk_mul_f32 v[52:53], v[64:65], v[244:245]
	v_pk_mul_f32 v[50:51], v[62:63], v[242:243]
	v_pk_mul_f32 v[56:57], v[60:61], v[248:249]
	v_pk_mul_f32 v[54:55], v[58:59], v[246:247]
	v_cvt_pk_bf16_f32 v50, v50, v51
	v_cvt_pk_bf16_f32 v51, v52, v53
	v_cvt_pk_bf16_f32 v52, v54, v55
	v_cvt_pk_bf16_f32 v53, v56, v57
	global_store_dwordx4 v[144:145], v[50:53], off offset:256
	ds_read_b32 v58, v183
	v_lshlrev_b64 v[60:61], 11, v[146:147]
	v_lshl_add_u64 v[60:61], s[4:5], 0, v[60:61]
	v_lshl_add_u64 v[60:61], v[60:61], 0, v[142:143]
	s_waitcnt lgkmcnt(0)
	v_pk_mul_f32 v[62:63], v[76:77], v[58:59] op_sel_hi:[1,0]
	v_pk_mul_f32 v[64:65], v[74:75], v[58:59] op_sel_hi:[1,0]
	v_pk_mul_f32 v[74:75], v[80:81], v[58:59] op_sel_hi:[1,0]
	v_pk_mul_f32 v[76:77], v[78:79], v[58:59] op_sel_hi:[1,0]
	v_pk_mul_f32 v[52:53], v[236:237], v[62:63]
	v_pk_mul_f32 v[50:51], v[234:235], v[64:65]
	v_pk_mul_f32 v[56:57], v[240:241], v[74:75]
	v_pk_mul_f32 v[54:55], v[238:239], v[76:77]
	v_cvt_pk_bf16_f32 v50, v50, v51
	v_cvt_pk_bf16_f32 v51, v52, v53
	v_cvt_pk_bf16_f32 v52, v54, v55
	v_cvt_pk_bf16_f32 v53, v56, v57
	global_store_dwordx4 v[60:61], v[50:53], off
	s_nop 0
	v_pk_mul_f32 v[62:63], v[96:97], v[58:59] op_sel_hi:[1,0]
	v_pk_mul_f32 v[64:65], v[94:95], v[58:59] op_sel_hi:[1,0]
	v_pk_mul_f32 v[74:75], v[92:93], v[58:59] op_sel_hi:[1,0]
	v_pk_mul_f32 v[58:59], v[90:91], v[58:59] op_sel_hi:[1,0]
	v_pk_mul_f32 v[52:53], v[62:63], v[244:245]
	v_pk_mul_f32 v[50:51], v[64:65], v[242:243]
	v_pk_mul_f32 v[56:57], v[74:75], v[248:249]
	v_pk_mul_f32 v[54:55], v[58:59], v[246:247]
	v_cvt_pk_bf16_f32 v50, v50, v51
	v_cvt_pk_bf16_f32 v51, v52, v53
	v_cvt_pk_bf16_f32 v52, v54, v55
	v_cvt_pk_bf16_f32 v53, v56, v57
	global_store_dwordx4 v[60:61], v[50:53], off offset:256
	ds_read_b32 v58, v184
	v_lshlrev_b64 v[60:61], 11, v[148:149]
	v_lshl_add_u64 v[60:61], s[4:5], 0, v[60:61]
	v_lshl_add_u64 v[60:61], v[60:61], 0, v[142:143]
	s_waitcnt lgkmcnt(0)
	v_pk_mul_f32 v[62:63], v[100:101], v[58:59] op_sel_hi:[1,0]
	v_pk_mul_f32 v[64:65], v[98:99], v[58:59] op_sel_hi:[1,0]
	v_pk_mul_f32 v[74:75], v[104:105], v[58:59] op_sel_hi:[1,0]
	v_pk_mul_f32 v[76:77], v[102:103], v[58:59] op_sel_hi:[1,0]
	v_pk_mul_f32 v[52:53], v[236:237], v[62:63]
	v_pk_mul_f32 v[50:51], v[234:235], v[64:65]
	v_pk_mul_f32 v[56:57], v[240:241], v[74:75]
	v_pk_mul_f32 v[54:55], v[238:239], v[76:77]
	v_cvt_pk_bf16_f32 v50, v50, v51
	v_cvt_pk_bf16_f32 v51, v52, v53
	v_cvt_pk_bf16_f32 v52, v54, v55
	v_cvt_pk_bf16_f32 v53, v56, v57
	global_store_dwordx4 v[60:61], v[50:53], off
	s_nop 0
	v_pk_mul_f32 v[62:63], v[120:121], v[58:59] op_sel_hi:[1,0]
	v_pk_mul_f32 v[64:65], v[118:119], v[58:59] op_sel_hi:[1,0]
	v_pk_mul_f32 v[74:75], v[116:117], v[58:59] op_sel_hi:[1,0]
	v_pk_mul_f32 v[58:59], v[114:115], v[58:59] op_sel_hi:[1,0]
	v_pk_mul_f32 v[52:53], v[62:63], v[244:245]
	v_pk_mul_f32 v[50:51], v[64:65], v[242:243]
	v_pk_mul_f32 v[56:57], v[74:75], v[248:249]
	v_pk_mul_f32 v[54:55], v[58:59], v[246:247]
	v_cvt_pk_bf16_f32 v50, v50, v51
	v_cvt_pk_bf16_f32 v51, v52, v53
	v_cvt_pk_bf16_f32 v52, v54, v55
	v_cvt_pk_bf16_f32 v53, v56, v57
	global_store_dwordx4 v[60:61], v[50:53], off offset:256
	ds_read_b32 v58, v185
	v_lshlrev_b64 v[60:61], 11, v[150:151]
	v_lshl_add_u64 v[60:61], s[4:5], 0, v[60:61]
	v_lshl_add_u64 v[60:61], v[60:61], 0, v[142:143]
	s_waitcnt lgkmcnt(0)
	v_pk_mul_f32 v[62:63], v[128:129], v[58:59] op_sel_hi:[1,0]
	v_pk_mul_f32 v[64:65], v[126:127], v[58:59] op_sel_hi:[1,0]
	v_pk_mul_f32 v[74:75], v[124:125], v[58:59] op_sel_hi:[1,0]
	v_pk_mul_f32 v[76:77], v[122:123], v[58:59] op_sel_hi:[1,0]
	v_pk_mul_f32 v[52:53], v[236:237], v[62:63]
	v_pk_mul_f32 v[50:51], v[234:235], v[64:65]
	v_pk_mul_f32 v[56:57], v[240:241], v[74:75]
	v_pk_mul_f32 v[54:55], v[238:239], v[76:77]
	v_cvt_pk_bf16_f32 v50, v50, v51
	v_cvt_pk_bf16_f32 v51, v52, v53
	v_cvt_pk_bf16_f32 v52, v54, v55
	v_cvt_pk_bf16_f32 v53, v56, v57
	global_store_dwordx4 v[60:61], v[50:53], off
	s_nop 0
	v_pk_mul_f32 v[62:63], v[112:113], v[58:59] op_sel_hi:[1,0]
	v_pk_mul_f32 v[64:65], v[110:111], v[58:59] op_sel_hi:[1,0]
	v_pk_mul_f32 v[74:75], v[108:109], v[58:59] op_sel_hi:[1,0]
	v_pk_mul_f32 v[58:59], v[106:107], v[58:59] op_sel_hi:[1,0]
	v_pk_mul_f32 v[52:53], v[62:63], v[244:245]
	v_pk_mul_f32 v[50:51], v[64:65], v[242:243]
	v_pk_mul_f32 v[56:57], v[74:75], v[248:249]
	v_pk_mul_f32 v[54:55], v[58:59], v[246:247]
	v_cvt_pk_bf16_f32 v50, v50, v51
	v_cvt_pk_bf16_f32 v51, v52, v53
	v_cvt_pk_bf16_f32 v52, v54, v55
	v_cvt_pk_bf16_f32 v53, v56, v57
	global_store_dwordx4 v[60:61], v[50:53], off offset:256
	ds_read_b32 v58, v186
	v_lshlrev_b64 v[60:61], 11, v[152:153]
	v_lshl_add_u64 v[60:61], s[4:5], 0, v[60:61]
	v_lshl_add_u64 v[60:61], v[60:61], 0, v[142:143]
	s_waitcnt lgkmcnt(0)
; __device__ __forceinline__ unsigned cvt_pk_bf16(float lo, float hi) { const f32x2 v = {lo, hi}; const bf16x2_t b = __builtin_convertvector(v, bf16x2_t); return __builtin_bit_cast(unsigned, b); }
;     __device__ __forceinline__ void operator()(f32x4 (&acc)[2][2][4][2], const Unit& u, int wr, int wc, int fr, int fq) const {
;     ...
;                 for (int m = 0; m < 4; ++m) { const int rl = ai * 128 + wr * 64 + m * 16 + fr; const float r2 = S[rl]; const size_t off = (size_t)(u.pm * 256 + rl) * DM + col0;
; #pragma unroll
;                     for (int bj = 0; bj < 2; ++bj) { const f32x4 ga = *(const f32x4*)(gnext + col0 + bj * 128), gb = *(const f32x4*)(gnext + col0 + bj * 128 + 4);
;                         const f32x4 v0 = acc[ai][bj][m][0] * r2 * ga, v1 = acc[ai][bj][m][1] * r2 * gb;
;                         u32x4 w; w.x = cvt_pk_bf16(v0[0], v0[1]); w.y = cvt_pk_bf16(v0[2], v0[3]); w.z = cvt_pk_bf16(v1[0], v1[1]); w.w = cvt_pk_bf16(v1[2], v1[3]);
;                         *(u32x4*)(XN + off + bj * 128) = w; }
;                     asm volatile("" ::: "memory"); }
	v_pk_mul_f32 v[62:63], v[88:89], v[58:59] op_sel_hi:[1,0]
	v_pk_mul_f32 v[64:65], v[86:87], v[58:59] op_sel_hi:[1,0]
	v_pk_mul_f32 v[74:75], v[84:85], v[58:59] op_sel_hi:[1,0]
	v_pk_mul_f32 v[76:77], v[82:83], v[58:59] op_sel_hi:[1,0]
	v_pk_mul_f32 v[68:69], v[68:69], v[58:59] op_sel_hi:[1,0]
	v_pk_mul_f32 v[52:53], v[236:237], v[62:63]
	v_pk_mul_f32 v[50:51], v[234:235], v[64:65]
	v_pk_mul_f32 v[56:57], v[240:241], v[74:75]
	v_pk_mul_f32 v[54:55], v[238:239], v[76:77]
	v_cvt_pk_bf16_f32 v50, v50, v51
	v_cvt_pk_bf16_f32 v51, v52, v53
	v_cvt_pk_bf16_f32 v52, v54, v55
	v_cvt_pk_bf16_f32 v53, v56, v57
	global_store_dwordx4 v[60:61], v[50:53], off
	s_nop 0
	v_pk_mul_f32 v[62:63], v[72:73], v[58:59] op_sel_hi:[1,0]
	v_pk_mul_f32 v[64:65], v[70:71], v[58:59] op_sel_hi:[1,0]
	v_pk_mul_f32 v[58:59], v[66:67], v[58:59] op_sel_hi:[1,0]
	v_pk_mul_f32 v[52:53], v[62:63], v[244:245]
	v_pk_mul_f32 v[50:51], v[64:65], v[242:243]
	v_pk_mul_f32 v[56:57], v[68:69], v[248:249]
	v_pk_mul_f32 v[54:55], v[58:59], v[246:247]
	v_cvt_pk_bf16_f32 v50, v50, v51
	v_cvt_pk_bf16_f32 v51, v52, v53
	v_cvt_pk_bf16_f32 v52, v54, v55
	v_cvt_pk_bf16_f32 v53, v56, v57
	global_store_dwordx4 v[60:61], v[50:53], off offset:256
	ds_read_b32 v58, v187
	v_lshlrev_b64 v[60:61], 11, v[156:157]
	v_lshl_add_u64 v[60:61], s[4:5], 0, v[60:61]
	v_lshl_add_u64 v[60:61], v[60:61], 0, v[142:143]
	s_waitcnt lgkmcnt(0)
	v_pk_mul_f32 v[48:49], v[48:49], v[58:59] op_sel_hi:[1,0]
	v_pk_mul_f32 v[46:47], v[46:47], v[58:59] op_sel_hi:[1,0]
	v_pk_mul_f32 v[44:45], v[44:45], v[58:59] op_sel_hi:[1,0]
	v_pk_mul_f32 v[42:43], v[42:43], v[58:59] op_sel_hi:[1,0]
	v_pk_mul_f32 v[40:41], v[40:41], v[58:59] op_sel_hi:[1,0]
	v_pk_mul_f32 v[38:39], v[38:39], v[58:59] op_sel_hi:[1,0]
	v_pk_mul_f32 v[36:37], v[36:37], v[58:59] op_sel_hi:[1,0]
	v_pk_mul_f32 v[34:35], v[34:35], v[58:59] op_sel_hi:[1,0]
	v_pk_mul_f32 v[48:49], v[236:237], v[48:49]
	v_pk_mul_f32 v[46:47], v[234:235], v[46:47]
	v_pk_mul_f32 v[50:51], v[240:241], v[44:45]
	v_pk_mul_f32 v[44:45], v[238:239], v[42:43]
	v_cvt_pk_bf16_f32 v42, v46, v47
	v_cvt_pk_bf16_f32 v43, v48, v49
	v_cvt_pk_bf16_f32 v44, v44, v45
	v_cvt_pk_bf16_f32 v45, v50, v51
	global_store_dwordx4 v[60:61], v[42:45], off
	s_nop 0
	v_pk_mul_f32 v[40:41], v[40:41], v[244:245]
	v_pk_mul_f32 v[38:39], v[38:39], v[242:243]
	v_pk_mul_f32 v[42:43], v[36:37], v[248:249]
	v_pk_mul_f32 v[36:37], v[34:35], v[246:247]
	v_cvt_pk_bf16_f32 v34, v38, v39
	v_cvt_pk_bf16_f32 v35, v40, v41
	v_cvt_pk_bf16_f32 v36, v36, v37
	v_cvt_pk_bf16_f32 v37, v42, v43
	global_store_dwordx4 v[60:61], v[34:37], off offset:256
	ds_read_b32 v42, v188
	v_lshlrev_b64 v[44:45], 11, v[166:167]
	v_lshl_add_u64 v[44:45], s[4:5], 0, v[44:45]
	v_lshl_add_u64 v[44:45], v[44:45], 0, v[142:143]
	s_waitcnt lgkmcnt(0)
	v_pk_mul_f32 v[32:33], v[32:33], v[42:43] op_sel_hi:[1,0]
	v_pk_mul_f32 v[30:31], v[30:31], v[42:43] op_sel_hi:[1,0]
	v_pk_mul_f32 v[28:29], v[28:29], v[42:43] op_sel_hi:[1,0]
	v_pk_mul_f32 v[26:27], v[26:27], v[42:43] op_sel_hi:[1,0]
	v_pk_mul_f32 v[24:25], v[24:25], v[42:43] op_sel_hi:[1,0]
	v_pk_mul_f32 v[22:23], v[22:23], v[42:43] op_sel_hi:[1,0]
	v_pk_mul_f32 v[20:21], v[20:21], v[42:43] op_sel_hi:[1,0]
	v_pk_mul_f32 v[18:19], v[18:19], v[42:43] op_sel_hi:[1,0]
	v_pk_mul_f32 v[32:33], v[236:237], v[32:33]
	v_pk_mul_f32 v[30:31], v[234:235], v[30:31]
	v_pk_mul_f32 v[34:35], v[240:241], v[28:29]
	v_pk_mul_f32 v[28:29], v[238:239], v[26:27]
	v_cvt_pk_bf16_f32 v26, v30, v31
	v_cvt_pk_bf16_f32 v27, v32, v33
	v_cvt_pk_bf16_f32 v28, v28, v29
	v_cvt_pk_bf16_f32 v29, v34, v35
	global_store_dwordx4 v[44:45], v[26:29], off
	s_nop 0
	v_pk_mul_f32 v[24:25], v[24:25], v[244:245]
	v_pk_mul_f32 v[22:23], v[22:23], v[242:243]
	v_pk_mul_f32 v[26:27], v[20:21], v[248:249]
	v_pk_mul_f32 v[20:21], v[18:19], v[246:247]
	v_cvt_pk_bf16_f32 v18, v22, v23
	v_cvt_pk_bf16_f32 v19, v24, v25
	v_cvt_pk_bf16_f32 v20, v20, v21
	v_cvt_pk_bf16_f32 v21, v26, v27
	global_store_dwordx4 v[44:45], v[18:21], off offset:256
	ds_read_b32 v26, v189
	v_lshlrev_b64 v[28:29], 11, v[168:169]
	v_lshl_add_u64 v[28:29], s[4:5], 0, v[28:29]
	v_lshl_add_u64 v[28:29], v[28:29], 0, v[142:143]
	s_waitcnt lgkmcnt(0)
	v_pk_mul_f32 v[16:17], v[16:17], v[26:27] op_sel_hi:[1,0]
	v_pk_mul_f32 v[14:15], v[14:15], v[26:27] op_sel_hi:[1,0]
	v_pk_mul_f32 v[12:13], v[12:13], v[26:27] op_sel_hi:[1,0]
	v_pk_mul_f32 v[10:11], v[10:11], v[26:27] op_sel_hi:[1,0]
	v_pk_mul_f32 v[8:9], v[8:9], v[26:27] op_sel_hi:[1,0]
	v_pk_mul_f32 v[6:7], v[6:7], v[26:27] op_sel_hi:[1,0]
	v_pk_mul_f32 v[4:5], v[4:5], v[26:27] op_sel_hi:[1,0]
	v_pk_mul_f32 v[2:3], v[2:3], v[26:27] op_sel_hi:[1,0]
	v_pk_mul_f32 v[16:17], v[236:237], v[16:17]
	v_pk_mul_f32 v[14:15], v[234:235], v[14:15]
	v_pk_mul_f32 v[18:19], v[240:241], v[12:13]
	v_pk_mul_f32 v[12:13], v[238:239], v[10:11]
	v_cvt_pk_bf16_f32 v10, v14, v15
	v_cvt_pk_bf16_f32 v11, v16, v17
	v_cvt_pk_bf16_f32 v12, v12, v13
	v_cvt_pk_bf16_f32 v13, v18, v19
	global_store_dwordx4 v[28:29], v[10:13], off
	s_nop 0
	v_pk_mul_f32 v[8:9], v[8:9], v[244:245]
	v_pk_mul_f32 v[6:7], v[6:7], v[242:243]
	v_pk_mul_f32 v[10:11], v[4:5], v[248:249]
	v_pk_mul_f32 v[4:5], v[2:3], v[246:247]
	v_cvt_pk_bf16_f32 v2, v6, v7
	v_cvt_pk_bf16_f32 v3, v8, v9
	v_cvt_pk_bf16_f32 v4, v4, v5
	v_cvt_pk_bf16_f32 v5, v10, v11
	global_store_dwordx4 v[28:29], v[2:5], off offset:256

;     __device__ __forceinline__ void operator()(f32x4 (&acc)[2][2][4][2], const Unit& u, int wr, int wc, int fr, int fq) const {
;     ...
; #pragma unroll
;         for (int ai = 0; ai < 2; ++ai)
; #pragma unroll
;             for (int m = 0; m < 4; ++m) { const int rl = ai * 128 + wr * 64 + m * 16 + fr; const float r1 = S[rl]; const size_t off = (size_t)(u.pm * 256 + rl) * DM + col0;
; #pragma unroll
;                 for (int bj = 0; bj < 2; ++bj) { const f32x4 xa = *(const f32x4*)(xin + off + bj * 128), xb = *(const f32x4*)(xin + off + bj * 128 + 4);
;                     const f32x4 ga = *(const f32x4*)(gpost + col0 + bj * 128), gb = *(const f32x4*)(gpost + col0 + bj * 128 + 4);
;                     const f32x4 v0 = xa + acc[ai][bj][m][0] * r1 * ga, v1 = xb + acc[ai][bj][m][1] * r1 * gb;
;                     *(f32x4*)(xout + off + bj * 128) = v0; *(f32x4*)(xout + off + bj * 128 + 4) = v1; acc[ai][bj][m][0] = v0; acc[ai][bj][m][1] = v1; }
;                 asm volatile("" ::: "memory"); }
.LBB0_235:
	s_or_b64 exec, exec, s[84:85]
	s_lshl_b32 s54, s82, 8
	v_add_u32_e32 v144, s54, v169
	v_lshl_or_b32 v142, s76, 8, v189
	v_ashrrev_i32_e32 v145, 31, v144
	v_ashrrev_i32_e32 v143, 31, v142
	v_lshlrev_b64 v[146:147], 10, v[144:145]
	v_lshl_add_u64 v[146:147], v[146:147], 0, v[142:143]
	v_lshlrev_b64 v[162:163], 2, v[146:147]
	v_lshl_add_u64 v[164:165], s[34:35], 0, v[162:163]
	v_lshl_add_u64 v[154:155], v[142:143], 2, s[52:53]
	global_load_dwordx4 v[218:221], v[154:155], off
	global_load_dwordx4 v[222:225], v[154:155], off offset:16
	global_load_dwordx4 v[226:229], v[154:155], off offset:512
	global_load_dwordx4 v[230:233], v[154:155], off offset:528
	s_waitcnt lgkmcnt(0)
	s_barrier
	ds_read_b32 v160, v181
	global_load_dwordx4 v[146:149], v[164:165], off offset:16
	global_load_dwordx4 v[150:153], v[164:165], off
	global_load_dwordx4 v[234:237], v[164:165], off offset:528
	global_load_dwordx4 v[238:241], v[164:165], off offset:512
	v_lshl_add_u64 v[162:163], s[14:15], 0, v[162:163]
	s_andn2_b64 vcc, exec, s[70:71]
	s_waitcnt lgkmcnt(0)
	v_pk_mul_f32 v[44:45], v[44:45], v[160:161] op_sel_hi:[1,0]
	v_pk_mul_f32 v[42:43], v[42:43], v[160:161] op_sel_hi:[1,0]
	v_pk_mul_f32 v[48:49], v[48:49], v[160:161] op_sel_hi:[1,0]
	v_pk_mul_f32 v[46:47], v[46:47], v[160:161] op_sel_hi:[1,0]
	v_pk_mul_f32 v[58:59], v[58:59], v[160:161] op_sel_hi:[1,0]
	v_pk_mul_f32 v[62:63], v[62:63], v[160:161] op_sel_hi:[1,0]
	v_pk_mul_f32 v[64:65], v[64:65], v[160:161] op_sel_hi:[1,0]
	v_pk_mul_f32 v[60:61], v[60:61], v[160:161] op_sel_hi:[1,0]
	s_waitcnt vmcnt(3)
	v_pk_fma_f32 v[48:49], v[48:49], v[224:225], v[148:149]
	s_waitcnt vmcnt(2)
	v_pk_fma_f32 v[44:45], v[220:221], v[44:45], v[152:153]
	v_pk_fma_f32 v[42:43], v[218:219], v[42:43], v[150:151]
	v_pk_fma_f32 v[46:47], v[46:47], v[222:223], v[146:147]
	global_store_dwordx4 v[162:163], v[42:45], off
	global_store_dwordx4 v[162:163], v[46:49], off offset:16
	s_waitcnt vmcnt(3)
	v_pk_fma_f32 v[58:59], v[58:59], v[230:231], v[234:235]
	v_add_u32_e32 v146, s54, v172
	v_ashrrev_i32_e32 v147, 31, v146
	s_waitcnt vmcnt(2)
	v_pk_fma_f32 v[62:63], v[62:63], v[226:227], v[238:239]
	v_lshlrev_b64 v[150:151], 10, v[146:147]
	v_pk_fma_f32 v[64:65], v[64:65], v[228:229], v[240:241]
	v_lshl_add_u64 v[150:151], v[150:151], 0, v[142:143]
	v_pk_fma_f32 v[60:61], v[60:61], v[232:233], v[236:237]
	global_store_dwordx4 v[162:163], v[62:65], off offset:512
	global_store_dwordx4 v[162:163], v[58:61], off offset:528
	v_lshlrev_b64 v[160:161], 2, v[150:151]
	v_lshl_add_u64 v[162:163], s[34:35], 0, v[160:161]
	ds_read_b32 v148, v182
	global_load_dwordx4 v[150:153], v[162:163], off offset:16
	global_load_dwordx4 v[156:159], v[162:163], off
	global_load_dwordx4 v[234:237], v[162:163], off offset:528
	global_load_dwordx4 v[238:241], v[162:163], off offset:512
	v_lshl_add_u64 v[160:161], s[14:15], 0, v[160:161]
	s_waitcnt lgkmcnt(0)
	v_pk_mul_f32 v[68:69], v[68:69], v[148:149] op_sel_hi:[1,0]
	v_pk_mul_f32 v[66:67], v[66:67], v[148:149] op_sel_hi:[1,0]
	v_pk_mul_f32 v[72:73], v[72:73], v[148:149] op_sel_hi:[1,0]
	v_pk_mul_f32 v[70:71], v[70:71], v[148:149] op_sel_hi:[1,0]
	v_pk_mul_f32 v[88:89], v[88:89], v[148:149] op_sel_hi:[1,0]
	v_pk_mul_f32 v[86:87], v[86:87], v[148:149] op_sel_hi:[1,0]
	v_pk_mul_f32 v[84:85], v[84:85], v[148:149] op_sel_hi:[1,0]
	v_pk_mul_f32 v[82:83], v[82:83], v[148:149] op_sel_hi:[1,0]
	v_add_u32_e32 v148, s54, v173
	v_ashrrev_i32_e32 v149, 31, v148
	s_waitcnt vmcnt(3)
	v_pk_fma_f32 v[72:73], v[72:73], v[224:225], v[152:153]
	s_waitcnt vmcnt(2)
	v_pk_fma_f32 v[68:69], v[220:221], v[68:69], v[158:159]
	v_pk_fma_f32 v[66:67], v[218:219], v[66:67], v[156:157]
	v_pk_fma_f32 v[70:71], v[70:71], v[222:223], v[150:151]
	global_store_dwordx4 v[160:161], v[66:69], off
	global_store_dwordx4 v[160:161], v[70:73], off offset:16
	s_waitcnt vmcnt(3)
	v_pk_fma_f32 v[84:85], v[84:85], v[232:233], v[236:237]
	v_lshlrev_b64 v[152:153], 10, v[148:149]
	s_waitcnt vmcnt(2)
	v_pk_fma_f32 v[88:89], v[88:89], v[228:229], v[240:241]
	v_pk_fma_f32 v[86:87], v[86:87], v[226:227], v[238:239]
	v_lshl_add_u64 v[152:153], v[152:153], 0, v[142:143]
	v_pk_fma_f32 v[82:83], v[82:83], v[230:231], v[234:235]
	global_store_dwordx4 v[160:161], v[86:89], off offset:512
	global_store_dwordx4 v[160:161], v[82:85], off offset:528
	v_lshlrev_b64 v[152:153], 2, v[152:153]
	v_lshl_add_u64 v[160:161], s[34:35], 0, v[152:153]
	ds_read_b32 v150, v183
	global_load_dwordx4 v[156:159], v[160:161], off offset:16
	global_load_dwordx4 v[202:205], v[160:161], off
	global_load_dwordx4 v[234:237], v[160:161], off offset:528
	global_load_dwordx4 v[238:241], v[160:161], off offset:512
	v_lshl_add_u64 v[152:153], s[14:15], 0, v[152:153]
	s_waitcnt lgkmcnt(0)
	v_pk_mul_f32 v[100:101], v[100:101], v[150:151] op_sel_hi:[1,0]
	v_pk_mul_f32 v[98:99], v[98:99], v[150:151] op_sel_hi:[1,0]
	v_pk_mul_f32 v[104:105], v[104:105], v[150:151] op_sel_hi:[1,0]
	v_pk_mul_f32 v[102:103], v[102:103], v[150:151] op_sel_hi:[1,0]
	v_pk_mul_f32 v[112:113], v[112:113], v[150:151] op_sel_hi:[1,0]
	v_pk_mul_f32 v[110:111], v[110:111], v[150:151] op_sel_hi:[1,0]
	v_pk_mul_f32 v[108:109], v[108:109], v[150:151] op_sel_hi:[1,0]
	v_pk_mul_f32 v[106:107], v[106:107], v[150:151] op_sel_hi:[1,0]
	v_add_u32_e32 v150, s54, v174
	v_ashrrev_i32_e32 v151, 31, v150
	s_waitcnt vmcnt(3)
	v_pk_fma_f32 v[104:105], v[104:105], v[224:225], v[158:159]
	s_waitcnt vmcnt(2)
	v_pk_fma_f32 v[100:101], v[220:221], v[100:101], v[204:205]
	v_pk_fma_f32 v[98:99], v[218:219], v[98:99], v[202:203]
	v_pk_fma_f32 v[102:103], v[102:103], v[222:223], v[156:157]
	global_store_dwordx4 v[152:153], v[98:101], off
	global_store_dwordx4 v[152:153], v[102:105], off offset:16
	s_waitcnt vmcnt(3)
;     __device__ __forceinline__ void operator()(f32x4 (&acc)[2][2][4][2], const Unit& u, int wr, int wc, int fr, int fq) const {
;     ...
; #pragma unroll
;         for (int ai = 0; ai < 2; ++ai)
; #pragma unroll
;             for (int m = 0; m < 4; ++m) { const int rl = ai * 128 + wr * 64 + m * 16 + fr; const float r1 = S[rl]; const size_t off = (size_t)(u.pm * 256 + rl) * DM + col0;
; #pragma unroll
;                 for (int bj = 0; bj < 2; ++bj) { const f32x4 xa = *(const f32x4*)(xin + off + bj * 128), xb = *(const f32x4*)(xin + off + bj * 128 + 4);
;                     const f32x4 ga = *(const f32x4*)(gpost + col0 + bj * 128), gb = *(const f32x4*)(gpost + col0 + bj * 128 + 4);
;                     const f32x4 v0 = xa + acc[ai][bj][m][0] * r1 * ga, v1 = xb + acc[ai][bj][m][1] * r1 * gb;
;                     *(f32x4*)(xout + off + bj * 128) = v0; *(f32x4*)(xout + off + bj * 128 + 4) = v1; acc[ai][bj][m][0] = v0; acc[ai][bj][m][1] = v1; }
;                 asm volatile("" ::: "memory"); }
	v_pk_fma_f32 v[106:107], v[106:107], v[230:231], v[234:235]
	v_lshlrev_b64 v[156:157], 10, v[150:151]
	s_waitcnt vmcnt(2)
	v_pk_fma_f32 v[112:113], v[112:113], v[228:229], v[240:241]
	v_pk_fma_f32 v[110:111], v[110:111], v[226:227], v[238:239]
	v_lshl_add_u64 v[156:157], v[156:157], 0, v[142:143]
	v_pk_fma_f32 v[108:109], v[108:109], v[232:233], v[236:237]
	global_store_dwordx4 v[152:153], v[110:113], off offset:512
	global_store_dwordx4 v[152:153], v[106:109], off offset:528
	v_lshlrev_b64 v[160:161], 2, v[156:157]
	v_lshl_add_u64 v[162:163], s[34:35], 0, v[160:161]
	ds_read_b32 v152, v184
	global_load_dwordx4 v[156:159], v[162:163], off offset:16
	global_load_dwordx4 v[202:205], v[162:163], off
	global_load_dwordx4 v[234:237], v[162:163], off offset:528
	global_load_dwordx4 v[238:241], v[162:163], off offset:512
	v_lshl_add_u64 v[160:161], s[14:15], 0, v[160:161]
	s_waitcnt lgkmcnt(0)
	v_pk_mul_f32 v[124:125], v[124:125], v[152:153] op_sel_hi:[1,0]
	v_pk_mul_f32 v[122:123], v[122:123], v[152:153] op_sel_hi:[1,0]
	v_pk_mul_f32 v[128:129], v[128:129], v[152:153] op_sel_hi:[1,0]
	v_pk_mul_f32 v[126:127], v[126:127], v[152:153] op_sel_hi:[1,0]
	v_pk_mul_f32 v[120:121], v[120:121], v[152:153] op_sel_hi:[1,0]
	v_pk_mul_f32 v[118:119], v[118:119], v[152:153] op_sel_hi:[1,0]
	v_pk_mul_f32 v[116:117], v[116:117], v[152:153] op_sel_hi:[1,0]
	v_pk_mul_f32 v[114:115], v[114:115], v[152:153] op_sel_hi:[1,0]
	v_add_u32_e32 v152, s54, v175
	v_ashrrev_i32_e32 v153, 31, v152
	s_waitcnt vmcnt(3)
	v_pk_fma_f32 v[128:129], v[128:129], v[224:225], v[158:159]
	s_waitcnt vmcnt(2)
	v_pk_fma_f32 v[124:125], v[220:221], v[124:125], v[204:205]
	v_pk_fma_f32 v[122:123], v[218:219], v[122:123], v[202:203]
	v_pk_fma_f32 v[126:127], v[126:127], v[222:223], v[156:157]
	global_store_dwordx4 v[160:161], v[122:125], off
	global_store_dwordx4 v[160:161], v[126:129], off offset:16
	s_waitcnt vmcnt(3)
	v_pk_fma_f32 v[116:117], v[116:117], v[232:233], v[236:237]
	v_lshlrev_b64 v[158:159], 10, v[152:153]
	s_waitcnt vmcnt(2)
	v_pk_fma_f32 v[120:121], v[120:121], v[228:229], v[240:241]
	v_pk_fma_f32 v[118:119], v[118:119], v[226:227], v[238:239]
	v_lshl_add_u64 v[158:159], v[158:159], 0, v[142:143]
	v_pk_fma_f32 v[114:115], v[114:115], v[230:231], v[234:235]
	global_store_dwordx4 v[160:161], v[118:121], off offset:512
	global_store_dwordx4 v[160:161], v[114:117], off offset:528
	v_lshlrev_b64 v[158:159], 2, v[158:159]
	v_lshl_add_u64 v[160:161], s[34:35], 0, v[158:159]
	ds_read_b32 v156, v185
	global_load_dwordx4 v[202:205], v[160:161], off offset:16
	global_load_dwordx4 v[206:209], v[160:161], off
	global_load_dwordx4 v[234:237], v[160:161], off offset:528
	global_load_dwordx4 v[238:241], v[160:161], off offset:512
	v_lshl_add_u64 v[158:159], s[14:15], 0, v[158:159]
	s_waitcnt lgkmcnt(0)
	v_pk_mul_f32 v[96:97], v[96:97], v[156:157] op_sel_hi:[1,0]
	v_pk_mul_f32 v[94:95], v[94:95], v[156:157] op_sel_hi:[1,0]
	v_pk_mul_f32 v[92:93], v[92:93], v[156:157] op_sel_hi:[1,0]
	v_pk_mul_f32 v[90:91], v[90:91], v[156:157] op_sel_hi:[1,0]
	v_pk_mul_f32 v[80:81], v[80:81], v[156:157] op_sel_hi:[1,0]
	v_pk_mul_f32 v[78:79], v[78:79], v[156:157] op_sel_hi:[1,0]
	v_pk_mul_f32 v[76:77], v[76:77], v[156:157] op_sel_hi:[1,0]
	v_pk_mul_f32 v[74:75], v[74:75], v[156:157] op_sel_hi:[1,0]
	v_add_u32_e32 v156, s54, v176
	v_ashrrev_i32_e32 v157, 31, v156
	s_waitcnt vmcnt(3)
	v_pk_fma_f32 v[92:93], v[92:93], v[224:225], v[204:205]
	s_waitcnt vmcnt(2)
	v_pk_fma_f32 v[96:97], v[220:221], v[96:97], v[208:209]
	v_pk_fma_f32 v[94:95], v[218:219], v[94:95], v[206:207]
	v_pk_fma_f32 v[90:91], v[90:91], v[222:223], v[202:203]
	global_store_dwordx4 v[158:159], v[94:97], off
	global_store_dwordx4 v[158:159], v[90:93], off offset:16
	v_lshlrev_b64 v[160:161], 10, v[156:157]
	v_lshl_add_u64 v[160:161], v[160:161], 0, v[142:143]
	v_lshlrev_b64 v[160:161], 2, v[160:161]
	v_lshl_add_u64 v[162:163], s[34:35], 0, v[160:161]
	v_lshl_add_u64 v[160:161], s[14:15], 0, v[160:161]
	s_waitcnt vmcnt(3)
	v_pk_fma_f32 v[76:77], v[76:77], v[232:233], v[236:237]
	s_waitcnt vmcnt(2)
	v_pk_fma_f32 v[80:81], v[80:81], v[228:229], v[240:241]
	v_pk_fma_f32 v[78:79], v[78:79], v[226:227], v[238:239]
	v_pk_fma_f32 v[74:75], v[74:75], v[230:231], v[234:235]
	global_store_dwordx4 v[158:159], v[78:81], off offset:512
	global_store_dwordx4 v[158:159], v[74:77], off offset:528
	ds_read_b32 v158, v186
	global_load_dwordx4 v[202:205], v[162:163], off offset:16
	global_load_dwordx4 v[206:209], v[162:163], off
	global_load_dwordx4 v[234:237], v[162:163], off offset:528
	global_load_dwordx4 v[238:241], v[162:163], off offset:512
	s_waitcnt lgkmcnt(0)
	v_pk_mul_f32 v[56:57], v[56:57], v[158:159] op_sel_hi:[1,0]
	v_pk_mul_f32 v[54:55], v[54:55], v[158:159] op_sel_hi:[1,0]
	v_pk_mul_f32 v[52:53], v[52:53], v[158:159] op_sel_hi:[1,0]
	v_pk_mul_f32 v[50:51], v[50:51], v[158:159] op_sel_hi:[1,0]
	v_pk_mul_f32 v[40:41], v[40:41], v[158:159] op_sel_hi:[1,0]
	v_pk_mul_f32 v[38:39], v[38:39], v[158:159] op_sel_hi:[1,0]
	v_pk_mul_f32 v[36:37], v[36:37], v[158:159] op_sel_hi:[1,0]
	v_pk_mul_f32 v[34:35], v[34:35], v[158:159] op_sel_hi:[1,0]
	v_add_u32_e32 v158, s54, v177
	v_ashrrev_i32_e32 v159, 31, v158
	s_waitcnt vmcnt(3)
	v_pk_fma_f32 v[52:53], v[52:53], v[224:225], v[204:205]
	s_waitcnt vmcnt(2)
	v_pk_fma_f32 v[56:57], v[220:221], v[56:57], v[208:209]
	v_pk_fma_f32 v[54:55], v[218:219], v[54:55], v[206:207]
	v_pk_fma_f32 v[50:51], v[50:51], v[222:223], v[202:203]
	global_store_dwordx4 v[160:161], v[54:57], off
	global_store_dwordx4 v[160:161], v[50:53], off offset:16
	s_waitcnt vmcnt(3)
	v_pk_fma_f32 v[36:37], v[36:37], v[232:233], v[236:237]
	s_waitcnt vmcnt(2)
; __device__ __forceinline__ float swap_add(float v) { auto rr = __builtin_amdgcn_permlane32_swap(__float_as_uint(v), __float_as_uint(v), false, false); return __uint_as_float(rr[0]) + __uint_as_float(rr[1]); }
;     __device__ __forceinline__ void exchange(const f32x4 (&acc)[2][2][4][2], const Unit& u, int e, int wr, int wc, int fr, int fq) const {
;     ...
;             for (int m = 0; m < 4; ++m) { float q = 0.f;
; #pragma unroll
;                 for (int bj = 0; bj < 2; ++bj)
; #pragma unroll
;                     for (int n = 0; n < 2; ++n) { const f32x4 v = acc[ai][bj][m][n]; q += (v[0] * v[0] + v[1] * v[1]) + (v[2] * v[2] + v[3] * v[3]); }
;                 q += __int_as_float(__builtin_amdgcn_ds_bpermute((lid ^ 16) << 2, __float_as_int(q))); q = swap_add(q);
;                 if (fq == 0) P[(ai * 128 + wr * 64 + m * 16 + fr) * 4 + wc] = q; }
;     __device__ __forceinline__ void operator()(f32x4 (&acc)[2][2][4][2], const Unit& u, int wr, int wc, int fr, int fq) const {
;     ...
; #pragma unroll
;         for (int ai = 0; ai < 2; ++ai)
; #pragma unroll
;             for (int m = 0; m < 4; ++m) { const int rl = ai * 128 + wr * 64 + m * 16 + fr; const float r1 = S[rl]; const size_t off = (size_t)(u.pm * 256 + rl) * DM + col0;
; #pragma unroll
;                 for (int bj = 0; bj < 2; ++bj) { const f32x4 xa = *(const f32x4*)(xin + off + bj * 128), xb = *(const f32x4*)(xin + off + bj * 128 + 4);
;                     const f32x4 ga = *(const f32x4*)(gpost + col0 + bj * 128), gb = *(const f32x4*)(gpost + col0 + bj * 128 + 4);
;                     const f32x4 v0 = xa + acc[ai][bj][m][0] * r1 * ga, v1 = xb + acc[ai][bj][m][1] * r1 * gb;
;                     *(f32x4*)(xout + off + bj * 128) = v0; *(f32x4*)(xout + off + bj * 128 + 4) = v1; acc[ai][bj][m][0] = v0; acc[ai][bj][m][1] = v1; }
;                 asm volatile("" ::: "memory"); }
	v_pk_fma_f32 v[40:41], v[40:41], v[228:229], v[240:241]
	v_pk_fma_f32 v[38:39], v[38:39], v[226:227], v[238:239]
	v_pk_fma_f32 v[34:35], v[34:35], v[230:231], v[234:235]
	global_store_dwordx4 v[160:161], v[38:41], off offset:512
	global_store_dwordx4 v[160:161], v[34:37], off offset:528
	v_lshlrev_b64 v[160:161], 10, v[158:159]
	v_lshl_add_u64 v[160:161], v[160:161], 0, v[142:143]
	v_lshlrev_b64 v[160:161], 2, v[160:161]
	v_lshl_add_u64 v[162:163], s[34:35], 0, v[160:161]
	ds_read_b32 v166, v187
	global_load_dwordx4 v[202:205], v[162:163], off offset:16
	global_load_dwordx4 v[206:209], v[162:163], off
	global_load_dwordx4 v[234:237], v[162:163], off offset:528
	global_load_dwordx4 v[238:241], v[162:163], off offset:512
	v_lshl_add_u64 v[160:161], s[14:15], 0, v[160:161]
	s_waitcnt lgkmcnt(0)
	v_pk_mul_f32 v[32:33], v[32:33], v[166:167] op_sel_hi:[1,0]
	v_pk_mul_f32 v[30:31], v[30:31], v[166:167] op_sel_hi:[1,0]
	v_pk_mul_f32 v[28:29], v[28:29], v[166:167] op_sel_hi:[1,0]
	v_pk_mul_f32 v[26:27], v[26:27], v[166:167] op_sel_hi:[1,0]
	v_pk_mul_f32 v[24:25], v[24:25], v[166:167] op_sel_hi:[1,0]
	v_pk_mul_f32 v[22:23], v[22:23], v[166:167] op_sel_hi:[1,0]
	v_pk_mul_f32 v[20:21], v[20:21], v[166:167] op_sel_hi:[1,0]
	v_pk_mul_f32 v[18:19], v[18:19], v[166:167] op_sel_hi:[1,0]
	v_add_u32_e32 v166, s54, v178
	v_ashrrev_i32_e32 v167, 31, v166
	s_waitcnt vmcnt(3)
	v_pk_fma_f32 v[28:29], v[28:29], v[224:225], v[204:205]
	s_waitcnt vmcnt(2)
	v_pk_fma_f32 v[32:33], v[220:221], v[32:33], v[208:209]
	v_pk_fma_f32 v[30:31], v[218:219], v[30:31], v[206:207]
	v_pk_fma_f32 v[26:27], v[26:27], v[222:223], v[202:203]
	global_store_dwordx4 v[160:161], v[30:33], off
	global_store_dwordx4 v[160:161], v[26:29], off offset:16
	s_waitcnt vmcnt(3)
	v_pk_fma_f32 v[20:21], v[20:21], v[232:233], v[236:237]
	s_waitcnt vmcnt(2)
	v_pk_fma_f32 v[24:25], v[24:25], v[228:229], v[240:241]
	v_pk_fma_f32 v[22:23], v[22:23], v[226:227], v[238:239]
	v_pk_fma_f32 v[18:19], v[18:19], v[230:231], v[234:235]
	global_store_dwordx4 v[160:161], v[22:25], off offset:512
	global_store_dwordx4 v[160:161], v[18:21], off offset:528
	v_lshlrev_b64 v[160:161], 10, v[166:167]
	v_lshl_add_u64 v[160:161], v[160:161], 0, v[142:143]
	v_lshlrev_b64 v[160:161], 2, v[160:161]
	v_lshl_add_u64 v[162:163], s[34:35], 0, v[160:161]
	ds_read_b32 v168, v188
	global_load_dwordx4 v[202:205], v[162:163], off offset:16
	global_load_dwordx4 v[206:209], v[162:163], off
	global_load_dwordx4 v[234:237], v[162:163], off offset:528
	global_load_dwordx4 v[238:241], v[162:163], off offset:512
	v_lshl_add_u64 v[160:161], s[14:15], 0, v[160:161]
	s_waitcnt lgkmcnt(0)
	v_pk_mul_f32 v[16:17], v[16:17], v[168:169] op_sel_hi:[1,0]
	v_pk_mul_f32 v[14:15], v[14:15], v[168:169] op_sel_hi:[1,0]
	v_pk_mul_f32 v[12:13], v[12:13], v[168:169] op_sel_hi:[1,0]
	v_pk_mul_f32 v[10:11], v[10:11], v[168:169] op_sel_hi:[1,0]
	v_pk_mul_f32 v[8:9], v[8:9], v[168:169] op_sel_hi:[1,0]
	v_pk_mul_f32 v[6:7], v[6:7], v[168:169] op_sel_hi:[1,0]
	v_pk_mul_f32 v[4:5], v[4:5], v[168:169] op_sel_hi:[1,0]
	v_pk_mul_f32 v[2:3], v[2:3], v[168:169] op_sel_hi:[1,0]
	s_waitcnt vmcnt(3)
	v_pk_fma_f32 v[12:13], v[12:13], v[224:225], v[204:205]
	s_waitcnt vmcnt(2)
	v_pk_fma_f32 v[16:17], v[220:221], v[16:17], v[208:209]
	v_pk_fma_f32 v[14:15], v[218:219], v[14:15], v[206:207]
	v_pk_fma_f32 v[10:11], v[10:11], v[222:223], v[202:203]
	global_store_dwordx4 v[160:161], v[14:17], off
	global_store_dwordx4 v[160:161], v[10:13], off offset:16
	s_waitcnt vmcnt(3)
	v_pk_fma_f32 v[4:5], v[4:5], v[232:233], v[236:237]
	s_waitcnt vmcnt(2)
	v_pk_fma_f32 v[8:9], v[8:9], v[228:229], v[240:241]
	v_pk_fma_f32 v[6:7], v[6:7], v[226:227], v[238:239]
	v_pk_fma_f32 v[2:3], v[2:3], v[230:231], v[234:235]
	global_store_dwordx4 v[160:161], v[6:9], off offset:512
	global_store_dwordx4 v[160:161], v[2:5], off offset:528
	s_cbranch_vccnz .LBB0_272
	v_mul_f32_e32 v154, v43, v43
	v_mul_f32_e32 v155, v45, v45
	v_fmac_f32_e32 v154, v42, v42
	v_fmac_f32_e32 v155, v44, v44
	v_add_f32_e32 v154, v154, v155
	v_mul_f32_e32 v155, v47, v47
	v_mul_f32_e32 v160, v49, v49
	v_fmac_f32_e32 v155, v46, v46
	v_fmac_f32_e32 v160, v48, v48
	v_add_f32_e32 v155, v155, v160
	v_add_f32_e32 v154, v154, v155
	v_mul_f32_e32 v155, v63, v63
	v_mul_f32_e32 v160, v65, v65
	v_fmac_f32_e32 v155, v62, v62
	v_fmac_f32_e32 v160, v64, v64
	v_add_f32_e32 v155, v155, v160
	v_add_f32_e32 v154, v154, v155
	v_mul_f32_e32 v155, v59, v59
	v_mul_f32_e32 v160, v61, v61
	v_fmac_f32_e32 v155, v58, v58
	v_fmac_f32_e32 v160, v60, v60
	v_add_f32_e32 v155, v155, v160
	v_add_f32_e32 v154, v154, v155
	ds_bpermute_b32 v155, v171, v154
	s_waitcnt lgkmcnt(0)
	v_add_f32_e32 v154, v154, v155
	v_mov_b32_e32 v155, v154
	s_nop 1
	v_permlane32_swap_b32_e32 v154, v155
	s_and_saveexec_b64 s[54:55], s[42:43]
	v_add_f32_e32 v154, v154, v155
	ds_write_b32 v191, v154
	s_or_b64 exec, exec, s[54:55]
	v_mul_f32_e32 v154, v67, v67
	v_mul_f32_e32 v155, v69, v69
	v_fmac_f32_e32 v154, v66, v66
	v_fmac_f32_e32 v155, v68, v68
	v_add_f32_e32 v154, v154, v155
	v_mul_f32_e32 v155, v71, v71
	v_mul_f32_e32 v160, v73, v73
	v_fmac_f32_e32 v155, v70, v70
	v_fmac_f32_e32 v160, v72, v72
	v_add_f32_e32 v155, v155, v160
	v_add_f32_e32 v154, v154, v155
	v_mul_f32_e32 v155, v87, v87
	v_mul_f32_e32 v160, v89, v89
	v_fmac_f32_e32 v155, v86, v86
	v_fmac_f32_e32 v160, v88, v88
	v_add_f32_e32 v155, v155, v160
	v_add_f32_e32 v154, v154, v155
	v_mul_f32_e32 v155, v83, v83
	v_mul_f32_e32 v160, v85, v85
	v_fmac_f32_e32 v155, v82, v82
	v_fmac_f32_e32 v160, v84, v84
	v_add_f32_e32 v155, v155, v160
	v_add_f32_e32 v154, v154, v155
	ds_bpermute_b32 v155, v171, v154
	s_waitcnt lgkmcnt(0)
; __device__ __forceinline__ float swap_add(float v) { auto rr = __builtin_amdgcn_permlane32_swap(__float_as_uint(v), __float_as_uint(v), false, false); return __uint_as_float(rr[0]) + __uint_as_float(rr[1]); }
;     __device__ __forceinline__ void exchange(const f32x4 (&acc)[2][2][4][2], const Unit& u, int e, int wr, int wc, int fr, int fq) const {
;     ...
;             for (int m = 0; m < 4; ++m) { float q = 0.f;
; #pragma unroll
;                 for (int bj = 0; bj < 2; ++bj)
; #pragma unroll
;                     for (int n = 0; n < 2; ++n) { const f32x4 v = acc[ai][bj][m][n]; q += (v[0] * v[0] + v[1] * v[1]) + (v[2] * v[2] + v[3] * v[3]); }
;                 q += __int_as_float(__builtin_amdgcn_ds_bpermute((lid ^ 16) << 2, __float_as_int(q))); q = swap_add(q);
;                 if (fq == 0) P[(ai * 128 + wr * 64 + m * 16 + fr) * 4 + wc] = q; }
;         __syncthreads();
;         float* xb = xbuf + (size_t)e * T * 4 + (size_t)u.pm * 256 * 4; unsigned* c = cnt + (e * 64 + u.pm) * 64;
;         if (tid < 256) { const float tot = (P[tid * 4] + P[tid * 4 + 1]) + (P[tid * 4 + 2] + P[tid * 4 + 3]);
;             __hip_atomic_store(xb + tid * 4 + u.pn, tot, __ATOMIC_RELAXED, __HIP_MEMORY_SCOPE_AGENT); }
	v_add_f32_e32 v154, v154, v155
	v_mov_b32_e32 v155, v154
	s_nop 1
	v_permlane32_swap_b32_e32 v154, v155
	s_and_saveexec_b64 s[54:55], s[42:43]
	v_add_f32_e32 v154, v154, v155
	ds_write_b32 v191, v154 offset:256
	s_or_b64 exec, exec, s[54:55]
	v_mul_f32_e32 v154, v99, v99
	v_mul_f32_e32 v155, v101, v101
	v_fmac_f32_e32 v154, v98, v98
	v_fmac_f32_e32 v155, v100, v100
	v_add_f32_e32 v154, v154, v155
	v_mul_f32_e32 v155, v103, v103
	v_mul_f32_e32 v160, v105, v105
	v_fmac_f32_e32 v155, v102, v102
	v_fmac_f32_e32 v160, v104, v104
	v_add_f32_e32 v155, v155, v160
	v_add_f32_e32 v154, v154, v155
	v_mul_f32_e32 v155, v111, v111
	v_mul_f32_e32 v160, v113, v113
	v_fmac_f32_e32 v155, v110, v110
	v_fmac_f32_e32 v160, v112, v112
	v_add_f32_e32 v155, v155, v160
	v_add_f32_e32 v154, v154, v155
	v_mul_f32_e32 v155, v107, v107
	v_mul_f32_e32 v160, v109, v109
	v_fmac_f32_e32 v155, v106, v106
	v_fmac_f32_e32 v160, v108, v108
	v_add_f32_e32 v155, v155, v160
	v_add_f32_e32 v154, v154, v155
	ds_bpermute_b32 v155, v171, v154
	s_waitcnt lgkmcnt(0)
	v_add_f32_e32 v154, v154, v155
	v_mov_b32_e32 v155, v154
	s_nop 1
	v_permlane32_swap_b32_e32 v154, v155
	s_and_saveexec_b64 s[54:55], s[42:43]
	v_add_f32_e32 v154, v154, v155
	ds_write_b32 v191, v154 offset:512
	s_or_b64 exec, exec, s[54:55]
	v_mul_f32_e32 v154, v123, v123
	v_mul_f32_e32 v155, v125, v125
	v_fmac_f32_e32 v154, v122, v122
	v_fmac_f32_e32 v155, v124, v124
	v_add_f32_e32 v154, v154, v155
	v_mul_f32_e32 v155, v127, v127
	v_mul_f32_e32 v160, v129, v129
	v_fmac_f32_e32 v155, v126, v126
	v_fmac_f32_e32 v160, v128, v128
	v_add_f32_e32 v155, v155, v160
	v_add_f32_e32 v154, v154, v155
	v_mul_f32_e32 v155, v119, v119
	v_mul_f32_e32 v160, v121, v121
	v_fmac_f32_e32 v155, v118, v118
	v_fmac_f32_e32 v160, v120, v120
	v_add_f32_e32 v155, v155, v160
	v_add_f32_e32 v154, v154, v155
	v_mul_f32_e32 v155, v115, v115
	v_mul_f32_e32 v160, v117, v117
	v_fmac_f32_e32 v155, v114, v114
	v_fmac_f32_e32 v160, v116, v116
	v_add_f32_e32 v155, v155, v160
	v_add_f32_e32 v154, v154, v155
	ds_bpermute_b32 v155, v171, v154
	s_waitcnt lgkmcnt(0)
	v_add_f32_e32 v154, v154, v155
	v_mov_b32_e32 v155, v154
	s_nop 1
	v_permlane32_swap_b32_e32 v154, v155
	s_and_saveexec_b64 s[54:55], s[42:43]
	v_add_f32_e32 v154, v154, v155
	ds_write_b32 v191, v154 offset:768
	s_or_b64 exec, exec, s[54:55]
	v_mul_f32_e32 v154, v95, v95
	v_mul_f32_e32 v155, v97, v97
	v_fmac_f32_e32 v154, v94, v94
	v_fmac_f32_e32 v155, v96, v96
	v_add_f32_e32 v154, v154, v155
	v_mul_f32_e32 v155, v91, v91
	v_mul_f32_e32 v160, v93, v93
	v_fmac_f32_e32 v155, v90, v90
	v_fmac_f32_e32 v160, v92, v92
	v_add_f32_e32 v155, v155, v160
	v_add_f32_e32 v154, v154, v155
	v_mul_f32_e32 v155, v79, v79
	v_mul_f32_e32 v160, v81, v81
	v_fmac_f32_e32 v155, v78, v78
	v_fmac_f32_e32 v160, v80, v80
	v_add_f32_e32 v155, v155, v160
	v_add_f32_e32 v154, v154, v155
	v_mul_f32_e32 v155, v75, v75
	v_mul_f32_e32 v160, v77, v77
	v_fmac_f32_e32 v155, v74, v74
	v_fmac_f32_e32 v160, v76, v76
	v_add_f32_e32 v155, v155, v160
	v_add_f32_e32 v154, v154, v155
	ds_bpermute_b32 v155, v171, v154
	s_waitcnt lgkmcnt(0)
	v_add_f32_e32 v154, v154, v155
	v_mov_b32_e32 v155, v154
	s_nop 1
	v_permlane32_swap_b32_e32 v154, v155
	s_and_saveexec_b64 s[54:55], s[42:43]
	v_add_f32_e32 v154, v154, v155
	ds_write_b32 v191, v154 offset:2048
	s_or_b64 exec, exec, s[54:55]
	v_mul_f32_e32 v154, v55, v55
	v_mul_f32_e32 v155, v57, v57
	v_fmac_f32_e32 v154, v54, v54
	v_fmac_f32_e32 v155, v56, v56
	v_add_f32_e32 v154, v154, v155
	v_mul_f32_e32 v155, v51, v51
	v_mul_f32_e32 v160, v53, v53
	v_fmac_f32_e32 v155, v50, v50
	v_fmac_f32_e32 v160, v52, v52
	v_add_f32_e32 v155, v155, v160
	v_add_f32_e32 v154, v154, v155
	v_mul_f32_e32 v155, v39, v39
	v_mul_f32_e32 v160, v41, v41
	v_fmac_f32_e32 v155, v38, v38
	v_fmac_f32_e32 v160, v40, v40
	v_add_f32_e32 v155, v155, v160
	v_add_f32_e32 v154, v154, v155
	v_mul_f32_e32 v155, v35, v35
	v_mul_f32_e32 v160, v37, v37
	v_fmac_f32_e32 v155, v34, v34
	v_fmac_f32_e32 v160, v36, v36
	v_add_f32_e32 v155, v155, v160
	v_add_f32_e32 v154, v154, v155
	ds_bpermute_b32 v155, v171, v154
	s_waitcnt lgkmcnt(0)
	v_add_f32_e32 v154, v154, v155
	v_mov_b32_e32 v155, v154
	s_nop 1
	v_permlane32_swap_b32_e32 v154, v155
	s_and_saveexec_b64 s[54:55], s[42:43]
	v_add_f32_e32 v154, v154, v155
	ds_write_b32 v191, v154 offset:2304
	s_or_b64 exec, exec, s[54:55]
	v_mul_f32_e32 v154, v31, v31
	v_mul_f32_e32 v155, v33, v33
	v_fmac_f32_e32 v154, v30, v30
	v_fmac_f32_e32 v155, v32, v32
	v_add_f32_e32 v154, v154, v155
	v_mul_f32_e32 v155, v27, v27
	v_mul_f32_e32 v160, v29, v29
	v_fmac_f32_e32 v155, v26, v26
	v_fmac_f32_e32 v160, v28, v28
	v_add_f32_e32 v155, v155, v160
	v_add_f32_e32 v154, v154, v155
	v_mul_f32_e32 v155, v23, v23
	v_mul_f32_e32 v160, v25, v25
	v_fmac_f32_e32 v155, v22, v22
	v_fmac_f32_e32 v160, v24, v24
	v_add_f32_e32 v155, v155, v160
	v_add_f32_e32 v154, v154, v155
	v_mul_f32_e32 v155, v19, v19
	v_mul_f32_e32 v160, v21, v21
	v_fmac_f32_e32 v155, v18, v18
	v_fmac_f32_e32 v160, v20, v20
	v_add_f32_e32 v155, v155, v160
	v_add_f32_e32 v154, v154, v155
	ds_bpermute_b32 v155, v171, v154
	s_waitcnt lgkmcnt(0)
	v_add_f32_e32 v154, v154, v155
	v_mov_b32_e32 v155, v154
	s_nop 1
	v_permlane32_swap_b32_e32 v154, v155
	s_and_saveexec_b64 s[54:55], s[42:43]
	v_add_f32_e32 v154, v154, v155
	ds_write_b32 v191, v154 offset:2560
	s_or_b64 exec, exec, s[54:55]
	v_mul_f32_e32 v154, v15, v15
	v_mul_f32_e32 v155, v17, v17
	v_fmac_f32_e32 v154, v14, v14
	v_fmac_f32_e32 v155, v16, v16
	v_add_f32_e32 v154, v154, v155
	v_mul_f32_e32 v155, v11, v11
	v_mul_f32_e32 v160, v13, v13
	v_fmac_f32_e32 v155, v10, v10
	v_fmac_f32_e32 v160, v12, v12
	v_add_f32_e32 v155, v155, v160
	v_add_f32_e32 v154, v154, v155
	v_mul_f32_e32 v155, v7, v7
	v_mul_f32_e32 v160, v9, v9
	v_fmac_f32_e32 v155, v6, v6
	v_fmac_f32_e32 v160, v8, v8
	v_add_f32_e32 v155, v155, v160
	v_add_f32_e32 v154, v154, v155
	v_mul_f32_e32 v155, v3, v3
	v_mul_f32_e32 v160, v5, v5
	v_fmac_f32_e32 v155, v2, v2
	v_fmac_f32_e32 v160, v4, v4
	v_add_f32_e32 v155, v155, v160
	v_add_f32_e32 v154, v154, v155
	ds_bpermute_b32 v155, v171, v154
	s_waitcnt lgkmcnt(0)
	v_add_f32_e32 v154, v154, v155
	v_mov_b32_e32 v155, v154
	s_nop 1
	v_permlane32_swap_b32_e32 v154, v155
	s_and_saveexec_b64 s[54:55], s[42:43]
	v_add_f32_e32 v154, v154, v155
	ds_write_b32 v191, v154 offset:2816
	s_or_b64 exec, exec, s[54:55]
	s_add_u32 s12, s97, s12
	s_addc_u32 s13, s72, s13
	v_lshl_add_u64 v[154:155], v[136:137], 2, s[12:13]
	s_waitcnt lgkmcnt(0)
	s_barrier
	s_and_saveexec_b64 s[12:13], s[44:45]
	s_cbranch_execz .LBB0_254
	ds_read_b128 v[202:205], v179
	s_ashr_i32 s77, s76, 31
	v_lshl_add_u64 v[162:163], s[76:77], 2, v[154:155]
	s_waitcnt lgkmcnt(0)
	v_mov_b32_e32 v160, v203
	v_mov_b32_e32 v161, v204
	v_mov_b32_e32 v203, v205
	v_pk_add_f32 v[160:161], v[160:161], v[202:203]
	s_nop 0
	v_pk_add_f32 v[160:161], v[160:161], v[160:161] op_sel:[0,1] op_sel_hi:[1,0]
	global_store_dword v[162:163], v160, off sc1

; __device__ __forceinline__ unsigned cvt_pk_bf16(float lo, float hi) { const f32x2 v = {lo, hi}; const bf16x2_t b = __builtin_convertvector(v, bf16x2_t); return __builtin_bit_cast(unsigned, b); }
;     __device__ __forceinline__ void operator()(f32x4 (&acc)[2][2][4][2], const Unit& u, int wr, int wc, int fr, int fq) const {
;     ...
;         if (gnext) {
;             exchange(acc, u, 1, wr, wc, fr, fq);
; #pragma unroll
;             for (int ai = 0; ai < 2; ++ai)
; #pragma unroll
;                 for (int m = 0; m < 4; ++m) { const int rl = ai * 128 + wr * 64 + m * 16 + fr; const float r2 = S[rl]; const size_t off = (size_t)(u.pm * 256 + rl) * DM + col0;
; #pragma unroll
;                     for (int bj = 0; bj < 2; ++bj) { const f32x4 ga = *(const f32x4*)(gnext + col0 + bj * 128), gb = *(const f32x4*)(gnext + col0 + bj * 128 + 4);
;                         const f32x4 v0 = acc[ai][bj][m][0] * r2 * ga, v1 = acc[ai][bj][m][1] * r2 * gb;
;                         u32x4 w; w.x = cvt_pk_bf16(v0[0], v0[1]); w.y = cvt_pk_bf16(v0[2], v0[3]); w.z = cvt_pk_bf16(v1[0], v1[1]); w.w = cvt_pk_bf16(v1[2], v1[3]);
;                         *(u32x4*)(XN + off + bj * 128) = w; }
;                     asm volatile("" ::: "memory"); }
.LBB0_271:
	s_or_b64 exec, exec, s[12:13]
	v_lshl_add_u64 v[154:155], v[142:143], 2, s[62:63]
	global_load_dwordx4 v[234:237], v[154:155], off
	global_load_dwordx4 v[238:241], v[154:155], off offset:16
	global_load_dwordx4 v[242:245], v[154:155], off offset:512
	global_load_dwordx4 v[246:249], v[154:155], off offset:528
	s_waitcnt lgkmcnt(0)
	s_barrier
	s_waitcnt vmcnt(0)
	ds_read_b32 v160, v181
	v_lshlrev_b64 v[144:145], 11, v[144:145]
	v_lshlrev_b64 v[142:143], 1, v[142:143]
	v_lshl_add_u64 v[144:145], s[4:5], 0, v[144:145]
	v_lshl_add_u64 v[144:145], v[144:145], 0, v[142:143]
	s_waitcnt lgkmcnt(0)
	v_pk_mul_f32 v[44:45], v[44:45], v[160:161] op_sel_hi:[1,0]
	v_pk_mul_f32 v[42:43], v[42:43], v[160:161] op_sel_hi:[1,0]
	v_pk_mul_f32 v[48:49], v[48:49], v[160:161] op_sel_hi:[1,0]
	v_pk_mul_f32 v[46:47], v[46:47], v[160:161] op_sel_hi:[1,0]
	v_pk_mul_f32 v[64:65], v[64:65], v[160:161] op_sel_hi:[1,0]
	v_pk_mul_f32 v[62:63], v[62:63], v[160:161] op_sel_hi:[1,0]
	v_pk_mul_f32 v[60:61], v[60:61], v[160:161] op_sel_hi:[1,0]
	v_pk_mul_f32 v[58:59], v[58:59], v[160:161] op_sel_hi:[1,0]
	v_pk_mul_f32 v[44:45], v[236:237], v[44:45]
	v_pk_mul_f32 v[42:43], v[234:235], v[42:43]
	v_pk_mul_f32 v[48:49], v[240:241], v[48:49]
	v_pk_mul_f32 v[46:47], v[238:239], v[46:47]
	v_cvt_pk_bf16_f32 v42, v42, v43
	v_cvt_pk_bf16_f32 v43, v44, v45
	v_cvt_pk_bf16_f32 v44, v46, v47
	v_cvt_pk_bf16_f32 v45, v48, v49
	global_store_dwordx4 v[144:145], v[42:45], off
	s_nop 0
	s_nop 0
	v_pk_mul_f32 v[44:45], v[64:65], v[244:245]
	v_pk_mul_f32 v[42:43], v[62:63], v[242:243]
	v_pk_mul_f32 v[48:49], v[60:61], v[248:249]
	v_pk_mul_f32 v[46:47], v[58:59], v[246:247]
	v_cvt_pk_bf16_f32 v42, v42, v43
	v_cvt_pk_bf16_f32 v43, v44, v45
	v_cvt_pk_bf16_f32 v44, v46, v47
	v_cvt_pk_bf16_f32 v45, v48, v49
	global_store_dwordx4 v[144:145], v[42:45], off offset:256
	ds_read_b32 v58, v182
	v_lshlrev_b64 v[60:61], 11, v[146:147]
	v_lshl_add_u64 v[60:61], s[4:5], 0, v[60:61]
	v_lshl_add_u64 v[60:61], v[60:61], 0, v[142:143]
	s_waitcnt lgkmcnt(0)
	v_pk_mul_f32 v[62:63], v[68:69], v[58:59] op_sel_hi:[1,0]
	v_pk_mul_f32 v[64:65], v[66:67], v[58:59] op_sel_hi:[1,0]
	v_pk_mul_f32 v[66:67], v[72:73], v[58:59] op_sel_hi:[1,0]
	v_pk_mul_f32 v[68:69], v[70:71], v[58:59] op_sel_hi:[1,0]
	v_pk_mul_f32 v[44:45], v[236:237], v[62:63]
	v_pk_mul_f32 v[42:43], v[234:235], v[64:65]
	v_pk_mul_f32 v[48:49], v[240:241], v[66:67]
	v_pk_mul_f32 v[46:47], v[238:239], v[68:69]
	v_cvt_pk_bf16_f32 v42, v42, v43
	v_cvt_pk_bf16_f32 v43, v44, v45
	v_cvt_pk_bf16_f32 v44, v46, v47
	v_cvt_pk_bf16_f32 v45, v48, v49
	global_store_dwordx4 v[60:61], v[42:45], off
	s_nop 0
	v_pk_mul_f32 v[62:63], v[88:89], v[58:59] op_sel_hi:[1,0]
	v_pk_mul_f32 v[64:65], v[86:87], v[58:59] op_sel_hi:[1,0]
	v_pk_mul_f32 v[66:67], v[84:85], v[58:59] op_sel_hi:[1,0]
	v_pk_mul_f32 v[58:59], v[82:83], v[58:59] op_sel_hi:[1,0]
	v_pk_mul_f32 v[44:45], v[62:63], v[244:245]
	v_pk_mul_f32 v[42:43], v[64:65], v[242:243]
	v_pk_mul_f32 v[48:49], v[66:67], v[248:249]
	v_pk_mul_f32 v[46:47], v[58:59], v[246:247]
	v_cvt_pk_bf16_f32 v42, v42, v43
	v_cvt_pk_bf16_f32 v43, v44, v45
	v_cvt_pk_bf16_f32 v44, v46, v47
	v_cvt_pk_bf16_f32 v45, v48, v49
	global_store_dwordx4 v[60:61], v[42:45], off offset:256
	ds_read_b32 v58, v183
	v_lshlrev_b64 v[60:61], 11, v[148:149]
	v_lshl_add_u64 v[60:61], s[4:5], 0, v[60:61]
	v_lshl_add_u64 v[60:61], v[60:61], 0, v[142:143]
	s_waitcnt lgkmcnt(0)
	v_pk_mul_f32 v[62:63], v[100:101], v[58:59] op_sel_hi:[1,0]
	v_pk_mul_f32 v[64:65], v[98:99], v[58:59] op_sel_hi:[1,0]
	v_pk_mul_f32 v[66:67], v[104:105], v[58:59] op_sel_hi:[1,0]
	v_pk_mul_f32 v[68:69], v[102:103], v[58:59] op_sel_hi:[1,0]
	v_pk_mul_f32 v[44:45], v[236:237], v[62:63]
	v_pk_mul_f32 v[42:43], v[234:235], v[64:65]
	v_pk_mul_f32 v[48:49], v[240:241], v[66:67]
	v_pk_mul_f32 v[46:47], v[238:239], v[68:69]
	v_cvt_pk_bf16_f32 v42, v42, v43
	v_cvt_pk_bf16_f32 v43, v44, v45
	v_cvt_pk_bf16_f32 v44, v46, v47
	v_cvt_pk_bf16_f32 v45, v48, v49
	global_store_dwordx4 v[60:61], v[42:45], off
	s_nop 0
	v_pk_mul_f32 v[62:63], v[112:113], v[58:59] op_sel_hi:[1,0]
	v_pk_mul_f32 v[64:65], v[110:111], v[58:59] op_sel_hi:[1,0]
	v_pk_mul_f32 v[66:67], v[108:109], v[58:59] op_sel_hi:[1,0]
	v_pk_mul_f32 v[58:59], v[106:107], v[58:59] op_sel_hi:[1,0]
	v_pk_mul_f32 v[44:45], v[62:63], v[244:245]
	v_pk_mul_f32 v[42:43], v[64:65], v[242:243]
	v_pk_mul_f32 v[48:49], v[66:67], v[248:249]
	v_pk_mul_f32 v[46:47], v[58:59], v[246:247]
	v_cvt_pk_bf16_f32 v42, v42, v43
	v_cvt_pk_bf16_f32 v43, v44, v45
	v_cvt_pk_bf16_f32 v44, v46, v47
	v_cvt_pk_bf16_f32 v45, v48, v49
	global_store_dwordx4 v[60:61], v[42:45], off offset:256
	ds_read_b32 v58, v184
	v_lshlrev_b64 v[60:61], 11, v[150:151]
	v_lshl_add_u64 v[60:61], s[4:5], 0, v[60:61]
	v_lshl_add_u64 v[60:61], v[60:61], 0, v[142:143]
	s_waitcnt lgkmcnt(0)
	v_pk_mul_f32 v[62:63], v[124:125], v[58:59] op_sel_hi:[1,0]
	v_pk_mul_f32 v[64:65], v[122:123], v[58:59] op_sel_hi:[1,0]
	v_pk_mul_f32 v[66:67], v[128:129], v[58:59] op_sel_hi:[1,0]
	v_pk_mul_f32 v[68:69], v[126:127], v[58:59] op_sel_hi:[1,0]
	v_pk_mul_f32 v[44:45], v[236:237], v[62:63]
	v_pk_mul_f32 v[42:43], v[234:235], v[64:65]
	v_pk_mul_f32 v[48:49], v[240:241], v[66:67]
	v_pk_mul_f32 v[46:47], v[238:239], v[68:69]
	v_cvt_pk_bf16_f32 v42, v42, v43
	v_cvt_pk_bf16_f32 v43, v44, v45
	v_cvt_pk_bf16_f32 v44, v46, v47
	v_cvt_pk_bf16_f32 v45, v48, v49
	global_store_dwordx4 v[60:61], v[42:45], off
	s_nop 0
	v_pk_mul_f32 v[62:63], v[120:121], v[58:59] op_sel_hi:[1,0]
	v_pk_mul_f32 v[64:65], v[118:119], v[58:59] op_sel_hi:[1,0]
	v_pk_mul_f32 v[66:67], v[116:117], v[58:59] op_sel_hi:[1,0]
	v_pk_mul_f32 v[58:59], v[114:115], v[58:59] op_sel_hi:[1,0]
	v_pk_mul_f32 v[44:45], v[62:63], v[244:245]
	v_pk_mul_f32 v[42:43], v[64:65], v[242:243]
	v_pk_mul_f32 v[48:49], v[66:67], v[248:249]
	v_pk_mul_f32 v[46:47], v[58:59], v[246:247]
	v_cvt_pk_bf16_f32 v42, v42, v43
	v_cvt_pk_bf16_f32 v43, v44, v45
	v_cvt_pk_bf16_f32 v44, v46, v47
	v_cvt_pk_bf16_f32 v45, v48, v49
	global_store_dwordx4 v[60:61], v[42:45], off offset:256
	ds_read_b32 v58, v185
	v_lshlrev_b64 v[60:61], 11, v[152:153]
	v_lshl_add_u64 v[60:61], s[4:5], 0, v[60:61]
	v_lshl_add_u64 v[60:61], v[60:61], 0, v[142:143]
	s_waitcnt lgkmcnt(0)
; __device__ __forceinline__ unsigned cvt_pk_bf16(float lo, float hi) { const f32x2 v = {lo, hi}; const bf16x2_t b = __builtin_convertvector(v, bf16x2_t); return __builtin_bit_cast(unsigned, b); }
;     __device__ __forceinline__ void operator()(f32x4 (&acc)[2][2][4][2], const Unit& u, int wr, int wc, int fr, int fq) const {
;     ...
;                 for (int m = 0; m < 4; ++m) { const int rl = ai * 128 + wr * 64 + m * 16 + fr; const float r2 = S[rl]; const size_t off = (size_t)(u.pm * 256 + rl) * DM + col0;
; #pragma unroll
;                     for (int bj = 0; bj < 2; ++bj) { const f32x4 ga = *(const f32x4*)(gnext + col0 + bj * 128), gb = *(const f32x4*)(gnext + col0 + bj * 128 + 4);
;                         const f32x4 v0 = acc[ai][bj][m][0] * r2 * ga, v1 = acc[ai][bj][m][1] * r2 * gb;
;                         u32x4 w; w.x = cvt_pk_bf16(v0[0], v0[1]); w.y = cvt_pk_bf16(v0[2], v0[3]); w.z = cvt_pk_bf16(v1[0], v1[1]); w.w = cvt_pk_bf16(v1[2], v1[3]);
;                         *(u32x4*)(XN + off + bj * 128) = w; }
;                     asm volatile("" ::: "memory"); }
	v_pk_mul_f32 v[62:63], v[96:97], v[58:59] op_sel_hi:[1,0]
	v_pk_mul_f32 v[64:65], v[94:95], v[58:59] op_sel_hi:[1,0]
	v_pk_mul_f32 v[66:67], v[92:93], v[58:59] op_sel_hi:[1,0]
	v_pk_mul_f32 v[68:69], v[90:91], v[58:59] op_sel_hi:[1,0]
	v_pk_mul_f32 v[44:45], v[236:237], v[62:63]
	v_pk_mul_f32 v[42:43], v[234:235], v[64:65]
	v_pk_mul_f32 v[48:49], v[240:241], v[66:67]
	v_pk_mul_f32 v[46:47], v[238:239], v[68:69]
	v_cvt_pk_bf16_f32 v42, v42, v43
	v_cvt_pk_bf16_f32 v43, v44, v45
	v_cvt_pk_bf16_f32 v44, v46, v47
	v_cvt_pk_bf16_f32 v45, v48, v49
	global_store_dwordx4 v[60:61], v[42:45], off
	s_nop 0
	v_pk_mul_f32 v[62:63], v[80:81], v[58:59] op_sel_hi:[1,0]
	v_pk_mul_f32 v[64:65], v[78:79], v[58:59] op_sel_hi:[1,0]
	v_pk_mul_f32 v[66:67], v[76:77], v[58:59] op_sel_hi:[1,0]
	v_pk_mul_f32 v[58:59], v[74:75], v[58:59] op_sel_hi:[1,0]
	v_pk_mul_f32 v[44:45], v[62:63], v[244:245]
	v_pk_mul_f32 v[42:43], v[64:65], v[242:243]
	v_pk_mul_f32 v[48:49], v[66:67], v[248:249]
	v_pk_mul_f32 v[46:47], v[58:59], v[246:247]
	v_cvt_pk_bf16_f32 v42, v42, v43
	v_cvt_pk_bf16_f32 v43, v44, v45
	v_cvt_pk_bf16_f32 v44, v46, v47
	v_cvt_pk_bf16_f32 v45, v48, v49
	global_store_dwordx4 v[60:61], v[42:45], off offset:256
	ds_read_b32 v58, v186
	v_lshlrev_b64 v[60:61], 11, v[156:157]
	v_lshl_add_u64 v[60:61], s[4:5], 0, v[60:61]
	v_lshl_add_u64 v[60:61], v[60:61], 0, v[142:143]
	s_waitcnt lgkmcnt(0)
	v_pk_mul_f32 v[56:57], v[56:57], v[58:59] op_sel_hi:[1,0]
	v_pk_mul_f32 v[54:55], v[54:55], v[58:59] op_sel_hi:[1,0]
	v_pk_mul_f32 v[52:53], v[52:53], v[58:59] op_sel_hi:[1,0]
	v_pk_mul_f32 v[50:51], v[50:51], v[58:59] op_sel_hi:[1,0]
	v_pk_mul_f32 v[40:41], v[40:41], v[58:59] op_sel_hi:[1,0]
	v_pk_mul_f32 v[38:39], v[38:39], v[58:59] op_sel_hi:[1,0]
	v_pk_mul_f32 v[36:37], v[36:37], v[58:59] op_sel_hi:[1,0]
	v_pk_mul_f32 v[34:35], v[34:35], v[58:59] op_sel_hi:[1,0]
	v_pk_mul_f32 v[44:45], v[236:237], v[56:57]
	v_pk_mul_f32 v[42:43], v[234:235], v[54:55]
	v_pk_mul_f32 v[48:49], v[240:241], v[52:53]
	v_pk_mul_f32 v[46:47], v[238:239], v[50:51]
	v_cvt_pk_bf16_f32 v42, v42, v43
	v_cvt_pk_bf16_f32 v43, v44, v45
	v_cvt_pk_bf16_f32 v44, v46, v47
	v_cvt_pk_bf16_f32 v45, v48, v49
	global_store_dwordx4 v[60:61], v[42:45], off
	s_nop 0
	v_pk_mul_f32 v[40:41], v[40:41], v[244:245]
	v_pk_mul_f32 v[38:39], v[38:39], v[242:243]
	v_pk_mul_f32 v[42:43], v[36:37], v[248:249]
	v_pk_mul_f32 v[36:37], v[34:35], v[246:247]
	v_cvt_pk_bf16_f32 v34, v38, v39
	v_cvt_pk_bf16_f32 v35, v40, v41
	v_cvt_pk_bf16_f32 v36, v36, v37
	v_cvt_pk_bf16_f32 v37, v42, v43
	global_store_dwordx4 v[60:61], v[34:37], off offset:256
	ds_read_b32 v42, v187
	v_lshlrev_b64 v[44:45], 11, v[158:159]
	v_lshl_add_u64 v[44:45], s[4:5], 0, v[44:45]
	v_lshl_add_u64 v[44:45], v[44:45], 0, v[142:143]
	s_waitcnt lgkmcnt(0)
	v_pk_mul_f32 v[32:33], v[32:33], v[42:43] op_sel_hi:[1,0]
	v_pk_mul_f32 v[30:31], v[30:31], v[42:43] op_sel_hi:[1,0]
	v_pk_mul_f32 v[28:29], v[28:29], v[42:43] op_sel_hi:[1,0]
	v_pk_mul_f32 v[26:27], v[26:27], v[42:43] op_sel_hi:[1,0]
	v_pk_mul_f32 v[24:25], v[24:25], v[42:43] op_sel_hi:[1,0]
	v_pk_mul_f32 v[22:23], v[22:23], v[42:43] op_sel_hi:[1,0]
	v_pk_mul_f32 v[20:21], v[20:21], v[42:43] op_sel_hi:[1,0]
	v_pk_mul_f32 v[18:19], v[18:19], v[42:43] op_sel_hi:[1,0]
	v_pk_mul_f32 v[32:33], v[236:237], v[32:33]
	v_pk_mul_f32 v[30:31], v[234:235], v[30:31]
	v_pk_mul_f32 v[34:35], v[240:241], v[28:29]
	v_pk_mul_f32 v[28:29], v[238:239], v[26:27]
	v_cvt_pk_bf16_f32 v26, v30, v31
	v_cvt_pk_bf16_f32 v27, v32, v33
	v_cvt_pk_bf16_f32 v28, v28, v29
	v_cvt_pk_bf16_f32 v29, v34, v35
	global_store_dwordx4 v[44:45], v[26:29], off
	s_nop 0
	v_pk_mul_f32 v[24:25], v[24:25], v[244:245]
	v_pk_mul_f32 v[22:23], v[22:23], v[242:243]
	v_pk_mul_f32 v[26:27], v[20:21], v[248:249]
	v_pk_mul_f32 v[20:21], v[18:19], v[246:247]
	v_cvt_pk_bf16_f32 v18, v22, v23
	v_cvt_pk_bf16_f32 v19, v24, v25
	v_cvt_pk_bf16_f32 v20, v20, v21
	v_cvt_pk_bf16_f32 v21, v26, v27
	global_store_dwordx4 v[44:45], v[18:21], off offset:256
	ds_read_b32 v26, v188
	v_lshlrev_b64 v[28:29], 11, v[166:167]
	v_lshl_add_u64 v[28:29], s[4:5], 0, v[28:29]
	v_lshl_add_u64 v[28:29], v[28:29], 0, v[142:143]
	s_waitcnt lgkmcnt(0)
	v_pk_mul_f32 v[16:17], v[16:17], v[26:27] op_sel_hi:[1,0]
	v_pk_mul_f32 v[14:15], v[14:15], v[26:27] op_sel_hi:[1,0]
	v_pk_mul_f32 v[12:13], v[12:13], v[26:27] op_sel_hi:[1,0]
	v_pk_mul_f32 v[10:11], v[10:11], v[26:27] op_sel_hi:[1,0]
	v_pk_mul_f32 v[8:9], v[8:9], v[26:27] op_sel_hi:[1,0]
	v_pk_mul_f32 v[6:7], v[6:7], v[26:27] op_sel_hi:[1,0]
	v_pk_mul_f32 v[4:5], v[4:5], v[26:27] op_sel_hi:[1,0]
	v_pk_mul_f32 v[2:3], v[2:3], v[26:27] op_sel_hi:[1,0]
	v_pk_mul_f32 v[16:17], v[236:237], v[16:17]
	v_pk_mul_f32 v[14:15], v[234:235], v[14:15]
	v_pk_mul_f32 v[18:19], v[240:241], v[12:13]
	v_pk_mul_f32 v[12:13], v[238:239], v[10:11]
	v_cvt_pk_bf16_f32 v10, v14, v15
	v_cvt_pk_bf16_f32 v11, v16, v17
	v_cvt_pk_bf16_f32 v12, v12, v13
	v_cvt_pk_bf16_f32 v13, v18, v19
	global_store_dwordx4 v[28:29], v[10:13], off
	s_nop 0
	v_pk_mul_f32 v[8:9], v[8:9], v[244:245]
	v_pk_mul_f32 v[6:7], v[6:7], v[242:243]
	v_pk_mul_f32 v[10:11], v[4:5], v[248:249]
	v_pk_mul_f32 v[4:5], v[2:3], v[246:247]
	v_cvt_pk_bf16_f32 v2, v6, v7
	v_cvt_pk_bf16_f32 v3, v8, v9
	v_cvt_pk_bf16_f32 v4, v4, v5
	v_cvt_pk_bf16_f32 v5, v10, v11
	global_store_dwordx4 v[28:29], v[2:5], off offset:256

; #define LAS __attribute__((address_space(3)))
; __device__ __forceinline__ float bf_lo(unsigned u) { return __uint_as_float(u << 16); }
; __device__ __forceinline__ float bf_hi(unsigned u) { return __uint_as_float(u & 0xffff0000u); }
; __device__ __forceinline__ int lane_op() { unsigned z = 0u; asm volatile("" : "+v"(z)); return (int)__builtin_amdgcn_mbcnt_hi(~0u, __builtin_amdgcn_mbcnt_lo(~0u, z)); }
; __device__ __forceinline__ float swap_add(float v) { auto rr = __builtin_amdgcn_permlane32_swap(__float_as_uint(v), __float_as_uint(v), false, false); return __uint_as_float(rr[0]) + __uint_as_float(rr[1]); }
; template <bool STORE> __device__ __forceinline__ void attn_unit(LAS unsigned char* lds, bf16_t* Q, const bf16_t* Kg, const bf16_t* VT, const float* subg, float lam, float outscale, int unit, const int wave_s) {
;     const int tid_ = wave_s * 64 + lane_op();
;     const int tid = tid_, lane = tid & 63, wid = wave_s, q = lane & 31, hi = lane >> 5;
;     const int bh = unit >> 4, qb = unit & 15, b = bh >> 3, h = bh & 7, map = wid >> 2;
;     const int qrow0 = qb * 128 + 32 * (wid & 3);
;     const int td = qrow0 >> 6;
;     bf16x8 qf[4];
;     { const bf16_t* Qp = Q + (size_t)(b * SEQ + qrow0 + q) * DM + h * 128 + map * 64 + 8 * hi;
; #pragma unroll
;       for (int d0 = 0; d0 < 4; ++d0) qf[d0] = *(const bf16x8*)(Qp + 16 * d0); }
;     const float sl = __int_as_float(__builtin_amdgcn_readfirstlane(__float_as_int(exp2f(-(float)(h + 1)) * LOG2E)));
;     float sself;
;     { const bf16_t* Kp = Kg + (size_t)(b * SEQ + qrow0 + q) * DM + h * 128 + map * 64 + 8 * hi; float a = 0.f;
; #pragma unroll
;       for (int d0 = 0; d0 < 4; ++d0) { const u32x4 kv = *(const u32x4*)(Kp + 16 * d0); const u32x4 qv = __builtin_bit_cast(u32x4, qf[d0]);
; #pragma unroll
;           for (int j = 0; j < 4; ++j) a += bf_lo(kv[j]) * bf_lo(qv[j]) + bf_hi(kv[j]) * bf_hi(qv[j]); }
;       sself = swap_add(a); }
.LBB0_576:
	s_lshl_b32 s12, s61, 5
	s_add_i32 s16, s61, s39
	s_add_i32 s18, s12, s60
	s_and_b64 s[12:13], s[46:47], exec
	s_cselect_b32 s13, s18, s16
	s_cmpk_gt_i32 s13, 0x3ff
	s_cbranch_scc1 .LBB0_575
	v_mov_b32_e32 v0, v1
	s_lshl_b32 s12, s13, 7
	v_mbcnt_lo_u32_b32 v0, -1, v0
	s_and_b32 s12, s12, 0x780
	v_readlane_b32 s16, v253, 8
	s_lshl_b32 s18, s13, 4
	v_mbcnt_hi_u32_b32 v219, -1, v0
	s_or_b32 s12, s12, s16
	s_and_b32 s34, s18, 0xfffff800
	v_and_b32_e32 v3, 31, v219
	s_or_b32 s62, s12, s34
	v_or_b32_e32 v4, s62, v3
	v_ashrrev_i32_e32 v5, 31, v4
	s_bfe_u32 s19, s13, 0x30004
	v_lshlrev_b64 v[4:5], 11, v[4:5]
	v_lshl_add_u64 v[6:7], s[48:49], 0, v[4:5]
	s_lshl_b32 s16, s19, 8
	v_readlane_b32 s13, v253, 6
	v_lshl_add_u64 v[4:5], s[50:51], 0, v[4:5]
	v_bfe_u32 v2, v219, 5, 1
	s_lshl_b32 s20, s13, 1
	s_mov_b32 s21, s17
	v_lshl_add_u64 v[4:5], v[4:5], 0, s[16:17]
	v_lshl_add_u64 v[6:7], v[6:7], 0, s[16:17]
	v_lshlrev_b32_e32 v0, 4, v2
	v_lshl_add_u64 v[4:5], v[4:5], 0, s[20:21]
	v_lshl_add_u64 v[6:7], v[6:7], 0, s[20:21]
	v_lshl_add_u64 v[18:19], v[4:5], 0, v[0:1]
	v_lshl_add_u64 v[16:17], v[6:7], 0, v[0:1]
	global_load_dwordx4 v[4:7], v[18:19], off
	global_load_dwordx4 v[144:147], v[16:17], off
	global_load_dwordx4 v[8:11], v[18:19], off offset:32
	global_load_dwordx4 v[148:151], v[16:17], off offset:32
	global_load_dwordx4 v[12:15], v[18:19], off offset:64
	global_load_dwordx4 v[152:155], v[16:17], off offset:64
	global_load_dwordx4 v[156:159], v[16:17], off offset:96
	s_nop 0
	global_load_dwordx4 v[16:19], v[18:19], off offset:96
	s_add_i32 s13, s19, 1
	v_cvt_f32_ubyte0_e32 v0, s13
	s_mov_b32 s13, 0x42fc0000
	v_cmp_lt_f32_e32 vcc, s13, v0
	v_mov_b32_e32 v20, 0x42800000
	s_lshl_b32 s63, s19, 7
	v_cndmask_b32_e32 v20, 0, v20, vcc
	v_sub_f32_e32 v0, v20, v0
	v_exp_f32_e32 v0, v0
	s_and_b64 s[20:21], vcc, exec
	s_cselect_b32 s13, 0xffffffc0, 0
	v_bfe_u32 v216, v219, 4, 2
	v_ldexp_f32 v0, v0, s13
	v_bfe_u32 v218, v219, 3, 3
	v_readfirstlane_b32 s13, v0
	v_mov_b32_e32 v179, v1
	v_bitop3_b32 v217, v216, v219, 7 bitop3:0x78
	s_ashr_i32 s35, s34, 31
	v_mov_b32_e32 v171, v1
	v_mov_b32_e32 v173, v1
	s_mov_b64 s[20:21], 0x20000
	s_waitcnt vmcnt(7)
	v_lshlrev_b32_e32 v0, 16, v4
	v_and_b32_e32 v4, 0xffff0000, v4
	s_waitcnt vmcnt(6)
	v_and_b32_e32 v21, 0xffff0000, v144
	v_lshlrev_b32_e32 v20, 16, v144
	v_lshlrev_b32_e32 v22, 16, v5
	v_and_b32_e32 v5, 0xffff0000, v5
	v_and_b32_e32 v24, 0xffff0000, v145
	v_mul_f32_e32 v4, v21, v4
	v_lshlrev_b32_e32 v23, 16, v145
	v_lshlrev_b32_e32 v25, 16, v6
	v_and_b32_e32 v6, 0xffff0000, v6
	v_and_b32_e32 v27, 0xffff0000, v146
	v_mul_f32_e32 v5, v24, v5
	v_fmac_f32_e32 v4, v20, v0
	v_lshlrev_b32_e32 v26, 16, v146
	v_lshlrev_b32_e32 v28, 16, v7
	v_and_b32_e32 v7, 0xffff0000, v7
	v_and_b32_e32 v30, 0xffff0000, v147
	v_mul_f32_e32 v6, v27, v6
	v_fmac_f32_e32 v5, v23, v22
	v_add_f32_e32 v0, 0, v4
	v_lshlrev_b32_e32 v29, 16, v147
	s_waitcnt vmcnt(5)
	v_lshlrev_b32_e32 v31, 16, v8
	v_and_b32_e32 v8, 0xffff0000, v8
	s_waitcnt vmcnt(4)
	v_and_b32_e32 v33, 0xffff0000, v148
	v_mul_f32_e32 v7, v30, v7
	v_fmac_f32_e32 v6, v26, v25
	v_add_f32_e32 v0, v5, v0
	v_lshlrev_b32_e32 v32, 16, v148
	v_lshlrev_b32_e32 v34, 16, v9
	v_and_b32_e32 v9, 0xffff0000, v9
	v_and_b32_e32 v36, 0xffff0000, v149
	v_mul_f32_e32 v8, v33, v8
	v_fmac_f32_e32 v7, v29, v28
	v_add_f32_e32 v0, v6, v0
	v_lshlrev_b32_e32 v35, 16, v149
	v_lshlrev_b32_e32 v37, 16, v10
	v_and_b32_e32 v10, 0xffff0000, v10
	v_and_b32_e32 v39, 0xffff0000, v150
	v_mul_f32_e32 v9, v36, v9
	v_fmac_f32_e32 v8, v32, v31
	v_add_f32_e32 v0, v7, v0
	v_lshlrev_b32_e32 v38, 16, v150
	v_lshlrev_b32_e32 v40, 16, v11
	v_and_b32_e32 v11, 0xffff0000, v11
	v_and_b32_e32 v42, 0xffff0000, v151
	v_mul_f32_e32 v10, v39, v10
	v_fmac_f32_e32 v9, v35, v34
	v_add_f32_e32 v0, v8, v0
	v_lshlrev_b32_e32 v41, 16, v151
	v_mul_f32_e32 v11, v42, v11
	v_fmac_f32_e32 v10, v38, v37
	v_add_f32_e32 v0, v9, v0
	s_waitcnt vmcnt(3)
	v_and_b32_e32 v6, 0xffff0000, v12
	s_waitcnt vmcnt(2)
	v_and_b32_e32 v7, 0xffff0000, v152
	v_fmac_f32_e32 v11, v41, v40
	v_add_f32_e32 v0, v10, v0
	v_lshlrev_b32_e32 v4, 16, v12
	v_lshlrev_b32_e32 v5, 16, v152
	v_mul_f32_e32 v6, v7, v6
	v_add_f32_e32 v0, v11, v0
	v_fmac_f32_e32 v6, v5, v4
	v_add_f32_e32 v0, v6, v0
	v_and_b32_e32 v6, 0xffff0000, v13
	v_and_b32_e32 v7, 0xffff0000, v153
	v_lshlrev_b32_e32 v4, 16, v13
	v_lshlrev_b32_e32 v5, 16, v153
	v_mul_f32_e32 v6, v7, v6
	v_fmac_f32_e32 v6, v5, v4
	v_and_b32_e32 v9, 0xffff0000, v15
	v_and_b32_e32 v8, 0xffff0000, v14
	v_and_b32_e32 v11, 0xffff0000, v155
	v_and_b32_e32 v10, 0xffff0000, v154
	v_add_f32_e32 v0, v6, v0
	v_lshlrev_b32_e32 v5, 16, v15
	v_lshlrev_b32_e32 v4, 16, v14
	v_lshlrev_b32_e32 v7, 16, v155
	v_lshlrev_b32_e32 v6, 16, v154
	v_pk_mul_f32 v[8:9], v[10:11], v[8:9]
	s_waitcnt vmcnt(1)
	v_and_b32_e32 v11, 0xffff0000, v157
	v_pk_fma_f32 v[4:5], v[6:7], v[4:5], v[8:9]
	s_waitcnt vmcnt(0)
; __device__ __forceinline__ float swap_add(float v) { auto rr = __builtin_amdgcn_permlane32_swap(__float_as_uint(v), __float_as_uint(v), false, false); return __uint_as_float(rr[0]) + __uint_as_float(rr[1]); }
; #define AT_ISSUE_K(tt) do { const unsigned so_ = (unsigned)(((tt) & 3) * AT_SLOT); const bf16_t* kp_ = kgp + (size_t)(tt) * 64 * DM; \
;         glds16(kp_, (unsigned)__builtin_amdgcn_readfirstlane(kdst + so_)); glds16(kp_ + kx1, (unsigned)__builtin_amdgcn_readfirstlane(kdst + so_ + 1024)); } while (0)
; #define AT_ISSUE_V(tt) do { const unsigned so_ = (unsigned)(((tt) & 3) * AT_SLOT); const bf16_t* vp_ = vgp + (tt) * 64; \
;         glds16(vp_, (unsigned)__builtin_amdgcn_readfirstlane(vdst + so_)); glds16(vp_ + vx1, (unsigned)__builtin_amdgcn_readfirstlane(vdst + so_ + 1024)); } while (0)
; #define AT_BAR(N) asm volatile("s_waitcnt vmcnt(" #N ") lgkmcnt(0)\n\ts_barrier" ::: "memory")
; template <bool STORE> __device__ __forceinline__ void attn_unit(LAS unsigned char* lds, bf16_t* Q, const bf16_t* Kg, const bf16_t* VT, const float* subg, float lam, float outscale, int unit, const int wave_s) {
;     ...
;       sself = swap_add(a); }
;     const unsigned lds0 = (unsigned)(uintptr_t)lds;
;     const bf16_t* kgp; const bf16_t* vgp;
;     { const int kr = 8 * wid + (lane >> 4), kc = (lane & 15) ^ (kr & 15); kgp = Kg + (size_t)(b * SEQ + kr) * DM + h * 128 + kc * 8;
;       const int vr = 16 * wid + (lane >> 3), vc = (lane & 7) ^ ((vr >> 1) & 7); vgp = VT + (size_t)(h * 128 + vr) * T + b * SEQ + vc * 8; }
;     const int kx1 = ((((lane & 15) ^ ((8 * wid + (lane >> 4) + 4) & 15)) - ((lane & 15) ^ ((8 * wid + (lane >> 4)) & 15))) * 8) + 4 * DM;
;     const int vx1 = ((((lane & 7) ^ (((16 * wid + (lane >> 3) + 8) >> 1) & 7)) - ((lane & 7) ^ (((16 * wid + (lane >> 3)) >> 1) & 7))) * 8) + 8 * T;
;     const unsigned kdst = lds0 + wid * 2048, vdst = lds0 + AT_VOFF + wid * 2048;
;     ...
;     AT_ISSUE_K(0); AT_ISSUE_V(0); AT_ISSUE_K(1); AT_ISSUE_V(1); AT_ISSUE_K(2); AT_ISSUE_V(2); AT_ISSUE_K(3);
;     AT_BAR(8);
;     f32x16 o[4]; o[0] = f32x16{}; o[1] = f32x16{}; o[2] = f32x16{}; o[3] = f32x16{};
;     float mref = sself + 6.0f, lsum = 0.f;
;     const int koff = q * 256 + (((map * 8 + hi) ^ (q & 15)) << 4), voff = AT_VOFF + q * 128 + ((hi ^ ((q >> 1) & 7)) << 4);
;     const float qposf = (float)(qrow0 + q - 4 * hi);
;     f32x16 x0, x1, n0, n1;
	v_and_b32_e32 v9, 0xffff0000, v17
	v_add_f32_e32 v0, v4, v0
	v_and_b32_e32 v8, 0xffff0000, v16
	v_and_b32_e32 v10, 0xffff0000, v156
	v_add_f32_e32 v0, v5, v0
	v_lshlrev_b32_e32 v5, 16, v17
	v_lshlrev_b32_e32 v4, 16, v16
	v_lshlrev_b32_e32 v7, 16, v157
	v_lshlrev_b32_e32 v6, 16, v156
	v_pk_mul_f32 v[8:9], v[10:11], v[8:9]
	v_and_b32_e32 v11, 0xffff0000, v159
	v_pk_fma_f32 v[4:5], v[6:7], v[4:5], v[8:9]
	v_and_b32_e32 v9, 0xffff0000, v19
	v_add_f32_e32 v0, v4, v0
	v_and_b32_e32 v8, 0xffff0000, v18
	v_and_b32_e32 v10, 0xffff0000, v158
	v_add_f32_e32 v0, v5, v0
	v_lshlrev_b32_e32 v5, 16, v19
	v_lshlrev_b32_e32 v4, 16, v18
	v_lshlrev_b32_e32 v7, 16, v159
	v_lshlrev_b32_e32 v6, 16, v158
	v_pk_mul_f32 v[8:9], v[10:11], v[8:9]
	v_and_b32_e32 v11, 15, v219
	v_pk_fma_f32 v[4:5], v[6:7], v[4:5], v[8:9]
	v_and_b32_e32 v8, 7, v219
	v_add_f32_e32 v0, v4, v0
	v_add_f32_e32 v0, v5, v0
	v_mov_b32_e32 v4, 0x3fb8aa3b
	v_mul_f32_e32 v166, s13, v4
	v_mov_b32_e32 v4, v0
	s_nop 1
	v_permlane32_swap_b32_e32 v0, v4
	v_readlane_b32 s13, v253, 23
	v_add_f32_e32 v10, v0, v4
	v_add_f32_e32 v169, 0x40c00000, v10
	v_or_b32_e32 v0, s13, v216
	v_add_u32_e32 v4, s34, v0
	v_ashrrev_i32_e32 v5, 31, v4
	v_bitop3_b32 v6, v216, 11, s13 bitop3:0xc8
	v_lshlrev_b64 v[4:5], 11, v[4:5]
	v_readlane_b32 s13, v253, 29
	v_bitop3_b32 v7, v0, v11, 11 bitop3:0x6c
	v_lshl_add_u64 v[4:5], s[50:51], 0, v[4:5]
	s_add_i32 s19, s63, s13
	v_lshl_add_u64 v[4:5], v[4:5], 0, s[16:17]
	v_lshlrev_b32_e32 v178, 4, v7
	v_or_b32_e32 v0, s19, v218
	v_lshl_add_u64 v[180:181], v[4:5], 0, v[178:179]
	v_lshlrev_b64 v[4:5], 15, v[0:1]
	v_lshl_add_u64 v[4:5], s[52:53], 0, v[4:5]
	v_lshl_add_u64 v[4:5], s[34:35], 1, v[4:5]
	v_lshlrev_b32_e32 v0, 4, v217
	v_lshl_add_u64 v[182:183], v[4:5], 0, v[0:1]
	v_bitop3_b32 v0, v6, v11, 4 bitop3:0x36
	v_sub_u32_e32 v0, v0, v7
	v_mov_b32_e32 v4, 0x1000
	v_lshl_add_u32 v170, v0, 3, v4
	v_bitop3_b32 v0, v216, v8, 4 bitop3:0x36
	v_sub_u32_e32 v0, v0, v217
	v_mov_b32_e32 v4, 0x20000
	v_lshl_add_u32 v172, v0, 3, v4
	v_lshlrev_b64 v[4:5], 1, v[170:171]
	s_mov_b32 s13, m0
	s_mov_b32 m0, s37
	s_nop 0
	global_load_lds_dwordx4 v[180:181], off
	s_mov_b32 m0, s13
	v_lshl_add_u64 v[6:7], v[180:181], 0, v[4:5]
	s_add_i32 s13, s37, 0x400
	s_mov_b32 s16, m0
	s_mov_b32 m0, s13
	s_nop 0
	global_load_lds_dwordx4 v[6:7], off
	s_mov_b32 m0, s16
	v_lshlrev_b64 v[6:7], 1, v[172:173]
	s_mov_b32 s13, m0
	s_mov_b32 m0, s3
	s_nop 0
	global_load_lds_dwordx4 v[182:183], off
	s_mov_b32 m0, s13
	v_lshl_add_u64 v[8:9], v[182:183], 0, v[6:7]
	s_add_i32 s13, s37, 0x10400
	s_mov_b32 s16, m0
	s_mov_b32 m0, s13
	s_nop 0
	global_load_lds_dwordx4 v[8:9], off
	s_mov_b32 m0, s16
	v_lshl_add_u64 v[8:9], v[180:181], 0, s[20:21]
	s_add_i32 s13, s37, 0x4000
	s_mov_b32 s16, m0
	s_mov_b32 m0, s13
	s_nop 0
	global_load_lds_dwordx4 v[8:9], off
	s_mov_b32 m0, s16
	v_lshl_add_u64 v[8:9], v[8:9], 0, v[4:5]
	s_add_i32 s13, s37, 0x4400
	s_mov_b32 s16, m0
	s_mov_b32 m0, s13
	s_nop 0
	global_load_lds_dwordx4 v[8:9], off
	s_mov_b32 m0, s16
	v_lshl_add_u64 v[8:9], v[182:183], 0, s[22:23]
	s_add_i32 s13, s37, 0x14000
	s_mov_b32 s16, m0
	s_mov_b32 m0, s13
	s_nop 0
	global_load_lds_dwordx4 v[8:9], off
	s_mov_b32 m0, s16
	v_lshl_add_u64 v[8:9], v[8:9], 0, v[6:7]
	s_add_i32 s13, s37, 0x14400
	s_mov_b32 s16, m0
	s_mov_b32 m0, s13
	s_nop 0
	global_load_lds_dwordx4 v[8:9], off
	s_mov_b32 m0, s16
	v_lshl_add_u64 v[8:9], v[180:181], 0, s[26:27]
	s_add_i32 s13, s37, 0x8000
	s_mov_b32 s16, m0
	s_mov_b32 m0, s13
	s_nop 0
	global_load_lds_dwordx4 v[8:9], off
	s_mov_b32 m0, s16
	v_lshl_add_u64 v[8:9], v[8:9], 0, v[4:5]
	s_add_i32 s13, s37, 0x8400
	s_mov_b32 s16, m0
	s_mov_b32 m0, s13
	s_nop 0
	global_load_lds_dwordx4 v[8:9], off
	s_mov_b32 m0, s16
	v_lshl_add_u64 v[8:9], v[182:183], 0, s[24:25]
	s_add_i32 s13, s37, 0x18000
	s_mov_b32 s16, m0
	s_mov_b32 m0, s13
	s_nop 0
	global_load_lds_dwordx4 v[8:9], off
	s_mov_b32 m0, s16
	v_lshl_add_u64 v[6:7], v[8:9], 0, v[6:7]
	s_mov_b64 s[20:21], 0x60000
	s_add_i32 s13, s37, 0x18400
	s_mov_b32 s16, m0
	s_mov_b32 m0, s13
	s_nop 0
	global_load_lds_dwordx4 v[6:7], off
	s_mov_b32 m0, s16
	v_lshl_add_u64 v[6:7], v[180:181], 0, s[20:21]
	s_add_i32 s13, s37, 0xc000
	s_mov_b32 s16, m0
	s_mov_b32 m0, s13
	s_nop 0
	global_load_lds_dwordx4 v[6:7], off
	s_mov_b32 m0, s16
	v_lshl_add_u64 v[4:5], v[6:7], 0, v[4:5]
	s_add_i32 s13, s37, 0xc400
	s_mov_b32 s16, m0
	s_mov_b32 m0, s13
	s_nop 0
	global_load_lds_dwordx4 v[4:5], off
	s_mov_b32 m0, s16
	v_or_b32_e32 v0, s12, v3
	v_lshlrev_b32_e32 v4, 2, v2
	v_sub_u32_e32 v0, v0, v4
	s_cmp_gt_u32 s12, 63
	v_cvt_f32_i32_e32 v205, v0
	s_cselect_b64 s[40:41], -1, 0
	s_cmp_lt_u32 s12, 64
	s_cselect_b64 s[20:21], -1, 0
	v_cndmask_b32_e64 v4, 1.0, 0, s[20:21]
	v_mul_f32_e32 v4, v4, v166
	v_mul_f32_e64 v5, -v205, v4
	v_mov_b32_e32 v168, v4
	v_add_f32_e32 v6, v4, v168
	v_sub_f32_e32 v8, v4, v168
	v_sub_f32_e32 v9, v5, v169
	v_readlane_b32 s13, v253, 24
	v_mov_b32_e32 v7, v9
	s_waitcnt vmcnt(8) lgkmcnt(0)
	s_barrier
; #define AT_DIAG(tt, c0, c1) do { const float base_ = qposf - (float)(64 * (tt)); \
;         _Pragma("unroll") for (int r = 0; r < 16; ++r) { const float cr_ = (float)((r & 3) + 8 * (r >> 2)); c0[r] -= sl * fabsf(base_ - cr_); c1[r] -= sl * fabsf(base_ - 32.f - cr_); } } while (0)
; #define AT_MAX(c0, c1, rm) do { float a_ = fmaxf(c0[0], c1[0]), b_ = fmaxf(c0[1], c1[1]); \
;         _Pragma("unroll") for (int r = 2; r < 16; r += 2) { a_ = max3f(a_, c0[r], c1[r]); b_ = max3f(b_, c0[r + 1], c1[r + 1]); } rm = swap_max(fmaxf(a_, b_)); } while (0)
; template <bool STORE> __device__ __forceinline__ void attn_unit(LAS unsigned char* lds, bf16_t* Q, const bf16_t* Kg, const bf16_t* VT, const float* subg, float lam, float outscale, int unit, const int wave_s) {
;     ...
;     { const float sg0 = td > 0 ? 1.f : 0.f;
;       AT_CINIT(0, sg0, x0, x1); AT_QK(0, x0, x1);
;       if (td == 0) AT_DIAG(0, x0, x1);
;       float rm; AT_MAX(x0, x1, rm);
	v_mov_b32_e32 v96, v9
	v_bitop3_b32 v38, v2, v11, s13 bitop3:0x36
	v_add_f32_e32 v10, v6, v6
	v_add_f32_e32 v11, v7, v7
	s_and_b64 vcc, exec, s[40:41]
	v_pk_fma_f32 v[12:13], v[6:7], 2.0, v[10:11] op_sel_hi:[1,0,1]
	s_nop 0
	v_pk_fma_f32 v[10:11], v[10:11], 2.0, v[12:13] op_sel_hi:[1,0,1]
	v_mov_b32_e32 v19, v12
	v_pk_fma_f32 v[10:11], v[12:13], 2.0, v[10:11] op_sel_hi:[1,0,1]
	s_nop 0
	v_mov_b32_e32 v5, v10
	v_add_f32_e32 v10, v4, v6
	v_add_f32_e32 v11, v5, v7
	v_mov_b32_e32 v5, v6
	v_pk_mov_b32 v[16:17], v[10:11], v[12:13] op_sel:[1,0]
	v_mov_b32_e32 v18, v10
	v_add_f32_e32 v16, v16, v10
	v_add_f32_e32 v17, v17, v11
	v_add_f32_e32 v12, v18, v9
	v_add_f32_e32 v13, v19, v9
	v_add_f32_e32 v26, v18, v17
	v_add_f32_e32 v27, v19, v17
	v_add_f32_e32 v24, v18, v13
	v_add_f32_e32 v25, v19, v13
	v_add_f32_e32 v6, v4, v9
	v_add_f32_e32 v7, v5, v9
	v_add_f32_e32 v32, v18, v25
	v_add_f32_e32 v33, v19, v25
	v_add_f32_e32 v18, v18, v27
	v_add_f32_e32 v19, v19, v27
	v_add_f32_e32 v14, v4, v11
	v_add_f32_e32 v15, v5, v11
	v_add_f32_e32 v20, v4, v13
	v_add_f32_e32 v21, v5, v13
	v_add_f32_e32 v22, v4, v17
	v_add_f32_e32 v23, v5, v17
	v_add_f32_e32 v28, v4, v25
	v_add_f32_e32 v29, v5, v25
	v_add_f32_e32 v30, v4, v27
	v_add_f32_e32 v31, v5, v27
	v_add_f32_e32 v34, v4, v33
	v_add_f32_e32 v35, v5, v33
	v_mov_b32_e32 v99, v12
	v_mov_b32_e32 v100, v13
	v_add_f32_e32 v12, v4, v19
	v_add_f32_e32 v13, v5, v19
	v_lshlrev_b32_e32 v4, 8, v3
	v_lshl_add_u32 v210, v38, 4, v4
	v_add_u32_e32 v208, 0, v210
	v_mov_b32_e32 v97, v6
	v_mov_b32_e32 v98, v7
	ds_read_b128 v[4:7], v208
	v_add_f32_e32 v36, v10, v33
	v_add_f32_e32 v37, v11, v32
	v_xor_b32_e32 v211, 32, v210
	v_mov_b32_e32 v101, v20
	v_mov_b32_e32 v102, v21
	v_mov_b32_e32 v103, v24
	v_mov_b32_e32 v104, v25
	v_mov_b32_e32 v105, v28
	v_mov_b32_e32 v106, v29
	v_mov_b32_e32 v107, v32
	v_mov_b32_e32 v108, v33
	v_mov_b32_e32 v109, v34
	v_mov_b32_e32 v110, v35
	v_mov_b32_e32 v111, v36
	v_add_u32_e32 v209, 0, v211
	v_add_f32_e32 v20, v10, v19
	v_add_f32_e32 v21, v11, v18
	v_mov_b32_e32 v80, v11
	ds_read_b128 v[8:11], v208 offset:8192
	s_waitcnt lgkmcnt(1)
	v_mfma_f32_32x32x16_bf16 v[96:111], v[4:7], v[144:147], v[96:111]
	ds_read_b128 v[4:7], v209
	v_mov_b32_e32 v81, v14
	v_mov_b32_e32 v82, v15
	v_mov_b32_e32 v83, v16
	v_mov_b32_e32 v84, v17
	v_mov_b32_e32 v85, v22
	v_mov_b32_e32 v86, v23
	v_mov_b32_e32 v87, v26
	v_mov_b32_e32 v88, v27
	v_mov_b32_e32 v89, v30
	v_mov_b32_e32 v90, v31
	v_mov_b32_e32 v91, v18
	v_mov_b32_e32 v92, v19
	v_mov_b32_e32 v93, v12
	v_mov_b32_e32 v94, v13
	v_mov_b32_e32 v95, v20
	s_waitcnt lgkmcnt(0)
	v_mfma_f32_32x32x16_bf16 v[96:111], v[4:7], v[148:151], v[96:111]
	ds_read_b128 v[4:7], v209 offset:8192
	v_xor_b32_e32 v212, 64, v210
	v_add_u32_e32 v206, 0, v212
	v_xor_b32_e32 v213, 0x60, v210
	v_add_u32_e32 v207, 0, v213
	v_mfma_f32_32x32x16_bf16 v[80:95], v[8:11], v[144:147], v[80:95]
	s_waitcnt lgkmcnt(0)
	v_mfma_f32_32x32x16_bf16 v[80:95], v[4:7], v[148:151], v[80:95]
	ds_read_b128 v[4:7], v206
	s_waitcnt lgkmcnt(0)
	v_mfma_f32_32x32x16_bf16 v[96:111], v[4:7], v[152:155], v[96:111]
	ds_read_b128 v[4:7], v206 offset:8192
	s_waitcnt lgkmcnt(0)
	v_mfma_f32_32x32x16_bf16 v[80:95], v[4:7], v[152:155], v[80:95]
	ds_read_b128 v[4:7], v207
	s_waitcnt lgkmcnt(0)
	v_mfma_f32_32x32x16_bf16 v[96:111], v[4:7], v[156:159], v[96:111]
	ds_read_b128 v[4:7], v207 offset:8192
	s_waitcnt lgkmcnt(0)
	v_mfma_f32_32x32x16_bf16 v[80:95], v[4:7], v[156:159], v[80:95]
	s_cbranch_vccnz .LBB0_579
; #define AT_DIAG(tt, c0, c1) do { const float base_ = qposf - (float)(64 * (tt)); \
;         _Pragma("unroll") for (int r = 0; r < 16; ++r) { const float cr_ = (float)((r & 3) + 8 * (r >> 2)); c0[r] -= sl * fabsf(base_ - cr_); c1[r] -= sl * fabsf(base_ - 32.f - cr_); } } while (0)
; template <bool STORE> __device__ __forceinline__ void attn_unit(LAS unsigned char* lds, bf16_t* Q, const bf16_t* Kg, const bf16_t* VT, const float* subg, float lam, float outscale, int unit, const int wave_s) {
;     ...
;     { const float sg0 = td > 0 ? 1.f : 0.f;
;       AT_CINIT(0, sg0, x0, x1); AT_QK(0, x0, x1);
;       if (td == 0) AT_DIAG(0, x0, x1);
	v_add_u32_e32 v4, -1, v0
	v_cvt_f32_i32_e32 v5, v4
	v_add_u32_e32 v4, -3, v0
	v_cvt_f32_i32_e32 v7, v4
	v_add_u32_e32 v4, -9, v0
	v_cvt_f32_i32_e32 v9, v4
	v_add_u32_e32 v4, -11, v0
	v_cvt_f32_i32_e32 v11, v4
	v_add_u32_e32 v4, -16, v0
	v_cvt_f32_i32_e32 v14, v4
	v_subrev_u32_e32 v4, 19, v0
	v_subrev_u32_e32 v13, 18, v0
	v_cvt_f32_i32_e32 v16, v13
	v_cvt_f32_i32_e32 v15, v4
	v_subrev_u32_e32 v4, 25, v0
	v_subrev_u32_e32 v13, 24, v0
	v_add_u32_e32 v6, -2, v0
	v_add_u32_e32 v8, -8, v0
	v_add_u32_e32 v10, -10, v0
	v_subrev_u32_e32 v12, 17, v0
	v_cvt_f32_i32_e32 v18, v13
	v_cvt_f32_i32_e32 v17, v4
	v_subrev_u32_e32 v4, 27, v0
	v_subrev_u32_e32 v13, 26, v0
	v_cvt_f32_i32_e32 v6, v6
	v_cvt_f32_i32_e32 v8, v8
	v_cvt_f32_i32_e32 v10, v10
	v_cvt_f32_i32_e32 v12, v12
	v_cvt_f32_i32_e32 v20, v13
	v_cvt_f32_i32_e32 v19, v4
	v_and_b32_e32 v4, 0x7fffffff, v205
	v_and_b32_e32 v5, 0x7fffffff, v5
	v_and_b32_e32 v7, 0x7fffffff, v7
	v_and_b32_e32 v6, 0x7fffffff, v6
	v_and_b32_e32 v9, 0x7fffffff, v9
	v_and_b32_e32 v8, 0x7fffffff, v8
	v_and_b32_e32 v11, 0x7fffffff, v11
	v_and_b32_e32 v10, 0x7fffffff, v10
	v_and_b32_e32 v13, 0x7fffffff, v12
	v_and_b32_e32 v12, 0x7fffffff, v14
	v_and_b32_e32 v15, 0x7fffffff, v15
	v_and_b32_e32 v14, 0x7fffffff, v16
	v_and_b32_e32 v17, 0x7fffffff, v17
	v_and_b32_e32 v16, 0x7fffffff, v18
	v_and_b32_e32 v19, 0x7fffffff, v19
	v_and_b32_e32 v18, 0x7fffffff, v20
	v_pk_fma_f32 v[110:111], v[166:167], v[18:19], v[110:111] op_sel_hi:[0,1,1] neg_lo:[1,0,0] neg_hi:[1,0,0]
	v_pk_fma_f32 v[108:109], v[166:167], v[16:17], v[108:109] op_sel_hi:[0,1,1] neg_lo:[1,0,0] neg_hi:[1,0,0]
	v_pk_fma_f32 v[106:107], v[166:167], v[14:15], v[106:107] op_sel_hi:[0,1,1] neg_lo:[1,0,0] neg_hi:[1,0,0]
	v_pk_fma_f32 v[104:105], v[166:167], v[12:13], v[104:105] op_sel_hi:[0,1,1] neg_lo:[1,0,0] neg_hi:[1,0,0]
	v_pk_fma_f32 v[102:103], v[166:167], v[10:11], v[102:103] op_sel_hi:[0,1,1] neg_lo:[1,0,0] neg_hi:[1,0,0]
	v_pk_fma_f32 v[100:101], v[166:167], v[8:9], v[100:101] op_sel_hi:[0,1,1] neg_lo:[1,0,0] neg_hi:[1,0,0]
	v_pk_fma_f32 v[98:99], v[166:167], v[6:7], v[98:99] op_sel_hi:[0,1,1] neg_lo:[1,0,0] neg_hi:[1,0,0]
	v_pk_fma_f32 v[96:97], v[166:167], v[4:5], v[96:97] op_sel_hi:[0,1,1] neg_lo:[1,0,0] neg_hi:[1,0,0]
	v_subrev_u32_e32 v4, 33, v0
	v_subrev_u32_e32 v5, 32, v0
	v_subrev_u32_e32 v6, 35, v0
	v_subrev_u32_e32 v7, 34, v0
	v_subrev_u32_e32 v8, 41, v0
	v_subrev_u32_e32 v9, 40, v0
	v_subrev_u32_e32 v10, 43, v0
	v_subrev_u32_e32 v11, 42, v0
	v_subrev_u32_e32 v12, 49, v0
	v_subrev_u32_e32 v13, 48, v0
	v_subrev_u32_e32 v14, 51, v0
	v_subrev_u32_e32 v15, 50, v0
	v_subrev_u32_e32 v16, 57, v0
	v_subrev_u32_e32 v17, 56, v0
	v_subrev_u32_e32 v18, 59, v0
	v_subrev_u32_e32 v0, 58, v0
	v_cvt_f32_i32_e32 v0, v0
	v_cvt_f32_i32_e32 v18, v18
	v_cvt_f32_i32_e32 v19, v17
	v_cvt_f32_i32_e32 v16, v16
	v_cvt_f32_i32_e32 v17, v15
	v_cvt_f32_i32_e32 v14, v14
	v_cvt_f32_i32_e32 v15, v13
	v_cvt_f32_i32_e32 v12, v12
	v_cvt_f32_i32_e32 v13, v11
	v_cvt_f32_i32_e32 v10, v10
	v_cvt_f32_i32_e32 v11, v9
	v_cvt_f32_i32_e32 v8, v8
	v_cvt_f32_i32_e32 v4, v4
	v_cvt_f32_i32_e32 v9, v5
	v_cvt_f32_i32_e32 v6, v6
	v_cvt_f32_i32_e32 v20, v7
	v_and_b32_e32 v5, 0x7fffffff, v4
	v_and_b32_e32 v4, 0x7fffffff, v9
	v_and_b32_e32 v7, 0x7fffffff, v6
	v_and_b32_e32 v6, 0x7fffffff, v20
	v_and_b32_e32 v9, 0x7fffffff, v8
	v_and_b32_e32 v8, 0x7fffffff, v11
	v_and_b32_e32 v11, 0x7fffffff, v10
	v_and_b32_e32 v10, 0x7fffffff, v13
	v_and_b32_e32 v13, 0x7fffffff, v12
	v_and_b32_e32 v12, 0x7fffffff, v15
	v_and_b32_e32 v15, 0x7fffffff, v14
	v_and_b32_e32 v14, 0x7fffffff, v17
	v_and_b32_e32 v17, 0x7fffffff, v16
	v_and_b32_e32 v16, 0x7fffffff, v19
	v_and_b32_e32 v19, 0x7fffffff, v18
	v_and_b32_e32 v18, 0x7fffffff, v0
	v_pk_fma_f32 v[94:95], v[166:167], v[18:19], v[94:95] op_sel_hi:[0,1,1] neg_lo:[1,0,0] neg_hi:[1,0,0]
	v_pk_fma_f32 v[92:93], v[166:167], v[16:17], v[92:93] op_sel_hi:[0,1,1] neg_lo:[1,0,0] neg_hi:[1,0,0]
	v_pk_fma_f32 v[90:91], v[166:167], v[14:15], v[90:91] op_sel_hi:[0,1,1] neg_lo:[1,0,0] neg_hi:[1,0,0]
	v_pk_fma_f32 v[88:89], v[166:167], v[12:13], v[88:89] op_sel_hi:[0,1,1] neg_lo:[1,0,0] neg_hi:[1,0,0]
	v_pk_fma_f32 v[86:87], v[166:167], v[10:11], v[86:87] op_sel_hi:[0,1,1] neg_lo:[1,0,0] neg_hi:[1,0,0]
	v_pk_fma_f32 v[84:85], v[166:167], v[8:9], v[84:85] op_sel_hi:[0,1,1] neg_lo:[1,0,0] neg_hi:[1,0,0]
	v_pk_fma_f32 v[82:83], v[166:167], v[6:7], v[82:83] op_sel_hi:[0,1,1] neg_lo:[1,0,0] neg_hi:[1,0,0]
	v_pk_fma_f32 v[80:81], v[166:167], v[4:5], v[80:81] op_sel_hi:[0,1,1] neg_lo:[1,0,0] neg_hi:[1,0,0]
